# merged P8 softmax: butterflies via exact permlane-swap / DPP register shuffles instead of ds_bpermute
# speedup vs baseline: 1.0024x; 1.0024x over previous
; #define LAS __attribute__((address_space(3)))
; #define VLOOP(t, N) for (int t##0_ = 2 * bid, t = min(t##0_ + vb, (N) - 1); t##0_ < (N); t##0_ += VG, t = min(t##0_ + vb, (N) - 1))
; template <int WT, class Epi>
; DEV void gemm_tile(const bf16_t* __restrict__ A, int lda, const bf16_t* __restrict__ Bt, int ldb, int K, unsigned char* lds, const Epi& epi) {
;     constexpr int FI = WT / 16;
;     constexpr int OPB = 2 * WT * 128;
;     constexpr int STB = 2 * OPB;
;     int tid = threadIdx.x & 255; asm volatile("" : "+v"(tid)); const int lane = tid & 63, wid = tid >> 6;
;     const int wr = wid >> 1, wc = wid & 1, fr = lane & 15, fq = lane >> 4;
;     f32x4 acc[FI][FI];
; #pragma unroll
;     for (int i = 0; i < FI; ++i)
; #pragma unroll
;         for (int j = 0; j < FI; ++j) acc[i][j] = (f32x4){0.f, 0.f, 0.f, 0.f};
;     const int lrow = tid >> 3, lcs = (tid & 7) ^ (lrow & 7);
;     const bf16_t* ap = A + (size_t)lrow * lda + lcs * 8;
;     const bf16_t* bp = Bt + (size_t)lrow * ldb + lcs * 8;
;     const unsigned l3a = (unsigned)(size_t)(LAS unsigned char*)lds;
;     const int nk = K >> 6;
;     ...
;     constexpr int NSTG = 65536 / STB;
; #pragma unroll
;     for (int s_ = 0; s_ < NSTG - 1; ++s_) if (s_ < nk) GLDS_STAGE(s_ * STB, s_);
;     const int aoff = (wr * WT + fr) * 128, boff = OPB + (wc * WT + fr) * 128, sw = fr & 7;
;     int cur = 0, nxt = (NSTG - 1) * STB;
;     for (int kt = 0; kt < nk; ++kt) {
;         if (NSTG == 4 && kt + 2 < nk) { if (FI == 2) asm volatile("s_waitcnt vmcnt(8)" ::: "memory"); else asm volatile("s_waitcnt vmcnt(0)" ::: "memory"); }
;         else asm volatile("s_waitcnt vmcnt(0)" ::: "memory");
;         __syncthreads();
;         if (kt + NSTG - 1 < nk) GLDS_STAGE(nxt, kt + NSTG - 1);
; __global__ void __launch_bounds__(512) hymba_fwd(Params p) {
;     ...
;         const int NS1 = 16 * 16 * 2;
;         VLOOP(t, NS1) { const int bhd = t >> 5, v = t & 31, mt = v >> 1, nt = v & 1, b = bhd >> 2, hd = bhd & 3;
;             EpiF32s e{sc + (size_t)(b * SEQ + mt * 128) * 1024 + hd * 256 + nt * 128, 1024, 0.04419417382415922f};
;             gemm_tile<64>(qx + (size_t)(b * SEQ + mt * 128) * LDB + hd * 512, LDB, mkb + (size_t)(b * 256 + nt * 128) * LDB + hd * 512, LDB, 512, vlds, e);
;         }
.LBB0_1295:
	s_ashr_i32 s14, s86, 7
	s_lshl_b32 s4, s86, 6
	s_lshl_b32 s76, s86, 7
	v_mov_b32_e32 v7, v1
	s_lshl_b32 s78, s14, 11
	s_and_b32 s79, s4, 0x780
	s_lshl_b32 s15, s86, 5
	s_and_b32 s77, s76, 0x80
	s_lshl_b32 s14, s14, 8
	s_or_b32 s76, s78, s79
	v_ashrrev_i32_e32 v13, 3, v7
	s_and_b32 s4, s15, 0xc00
	s_or_b32 s14, s14, s77
	v_lshrrev_b32_e32 v4, 4, v7
	v_and_b32_e32 v6, 15, v7
	v_ashrrev_i32_e32 v15, 1, v7
	v_lshlrev_b32_e32 v16, 7, v7
	v_and_b32_e32 v17, 7, v7
	v_mad_i64_i32 v[8:9], s[78:79], s76, v12, v[132:133]
	v_xor_b32_e32 v18, v13, v7
	v_lshlrev_b32_e32 v14, 4, v7
	v_mad_i64_i32 v[10:11], s[78:79], s14, v12, v[168:169]
	v_and_or_b32 v6, v15, s85, v6
	v_and_b32_e32 v15, 0x2780, v16
	v_bitop3_b32 v4, v4, v17, 3 bitop3:0x6c
	v_lshl_add_u64 v[8:9], v[8:9], 0, s[4:5]
	v_lshlrev_b32_e32 v16, 4, v18
	v_add_u32_e32 v19, s80, v14
	v_add_u32_e32 v106, 0x4000, v14
	v_add_u32_e32 v14, s81, v14
	v_lshl_add_u64 v[10:11], v[10:11], 0, s[4:5]
	v_lshlrev_b32_e32 v20, 4, v4
	v_mad_i64_i32 v[8:9], s[86:87], v13, s84, v[8:9]
	v_and_b32_e32 v4, 0x70, v16
	v_add_u32_e32 v18, 0x4000, v19
	v_readfirstlane_b32 s92, v19
	v_readfirstlane_b32 s78, v14
	v_add_u32_e32 v87, s80, v15
	v_mad_i64_i32 v[14:15], s[86:87], v13, s84, v[10:11]
	v_lshl_add_u64 v[10:11], v[8:9], 0, v[4:5]
	s_mov_b32 vcc_lo, m0
	s_mov_b32 m0, s92
	s_nop 0
	global_load_lds_dwordx4 v[10:11], off
	s_mov_b32 m0, vcc_lo
	v_readfirstlane_b32 s14, v18
	v_lshl_add_u64 v[8:9], v[14:15], 0, v[4:5]
	s_mov_b32 vcc_lo, m0
	s_mov_b32 m0, s14
	s_nop 0
	global_load_lds_dwordx4 v[8:9], off
	s_mov_b32 m0, vcc_lo
	v_add_u32_e32 v19, s81, v106
	s_add_i32 s95, s92, 0x1000
	s_add_i32 s15, s14, 0x1000
	s_add_i32 s96, s14, 0x2000
	s_add_i32 s97, s14, 0x3000
	v_lshl_add_u64 v[14:15], v[10:11], 0, s[6:7]
	s_mov_b32 s14, m0
	s_mov_b32 m0, s95
	s_nop 0
	global_load_lds_dwordx4 v[14:15], off
	s_mov_b32 m0, s14
	v_lshl_add_u32 v86, v6, 7, s80
	v_readfirstlane_b32 s88, v19
	v_lshl_add_u64 v[18:19], v[8:9], 0, s[6:7]
	s_mov_b32 s14, m0
	s_mov_b32 m0, s15
	s_nop 0
	global_load_lds_dwordx4 v[18:19], off
	s_mov_b32 m0, s14
	s_add_i32 s94, s92, 0x2000
	v_add_u32_e32 v13, v86, v20
	v_add_u32_e32 v16, v87, v20
	v_lshl_add_u64 v[20:21], v[10:11], 0, s[8:9]
	s_mov_b32 s14, m0
	s_mov_b32 m0, s94
	s_nop 0
	global_load_lds_dwordx4 v[20:21], off
	s_mov_b32 m0, s14
	v_lshl_add_u64 v[22:23], v[8:9], 0, s[8:9]
	s_mov_b32 s14, m0
	s_mov_b32 m0, s96
	s_nop 0
	global_load_lds_dwordx4 v[22:23], off
	s_mov_b32 m0, s14
	s_add_i32 s93, s92, 0x3000
	v_lshl_add_u64 v[24:25], v[10:11], 0, s[10:11]
	s_mov_b32 s14, m0
	s_mov_b32 m0, s93
	s_nop 0
	global_load_lds_dwordx4 v[24:25], off
	s_mov_b32 m0, s14
	v_lshl_add_u64 v[26:27], v[8:9], 0, s[10:11]
	s_mov_b32 s14, m0
	s_mov_b32 m0, s97
	s_nop 0
	global_load_lds_dwordx4 v[26:27], off
	s_mov_b32 m0, s14
	v_lshl_add_u64 v[28:29], v[10:11], 0, s[12:13]
	s_waitcnt vmcnt(0)
	s_barrier
	s_mov_b32 s14, m0
	s_mov_b32 m0, s78
	s_nop 0
	global_load_lds_dwordx4 v[28:29], off
	s_mov_b32 m0, s14
	v_lshl_add_u64 v[30:31], v[8:9], 0, s[12:13]
	s_mov_b32 s14, m0
	s_mov_b32 m0, s88
	s_nop 0
	global_load_lds_dwordx4 v[30:31], off
	s_mov_b32 m0, s14
	s_add_i32 s87, s78, 0x1000
	v_lshl_add_u64 v[32:33], v[10:11], 0, s[16:17]
	s_mov_b32 s14, m0
	s_mov_b32 m0, s87
	s_nop 0
	global_load_lds_dwordx4 v[32:33], off
	s_mov_b32 m0, s14
	s_add_i32 s91, s88, 0x1000
	v_lshl_add_u64 v[34:35], v[8:9], 0, s[16:17]
	s_mov_b32 s14, m0
	s_mov_b32 m0, s91
	s_nop 0
	global_load_lds_dwordx4 v[34:35], off
	s_mov_b32 m0, s14
	s_add_i32 s86, s78, 0x2000
	v_lshl_add_u64 v[36:37], v[10:11], 0, s[18:19]
	s_mov_b32 s14, m0
	s_mov_b32 m0, s86
	s_nop 0
	global_load_lds_dwordx4 v[36:37], off
	s_mov_b32 m0, s14
	s_add_i32 s90, s88, 0x2000
	v_lshl_add_u64 v[38:39], v[8:9], 0, s[18:19]
	s_mov_b32 s14, m0
	s_mov_b32 m0, s90
	s_nop 0
	global_load_lds_dwordx4 v[38:39], off
	s_mov_b32 m0, s14
	s_add_i32 s79, s78, 0x3000
	v_lshl_add_u64 v[40:41], v[10:11], 0, s[20:21]
	s_mov_b32 s14, m0
	s_mov_b32 m0, s79
	s_nop 0
	global_load_lds_dwordx4 v[40:41], off
	s_mov_b32 m0, s14
	s_add_i32 s89, s88, 0x3000
	v_lshl_add_u64 v[42:43], v[8:9], 0, s[20:21]
	s_mov_b32 s14, m0
	s_mov_b32 m0, s89
	s_nop 0
	global_load_lds_dwordx4 v[42:43], off
	s_mov_b32 m0, s14
	ds_read_b128 v[18:21], v16 offset:16384
	ds_read_b128 v[22:25], v16 offset:18432
	ds_read_b128 v[26:29], v13
	ds_read_b128 v[30:33], v13 offset:2048
	ds_read_b128 v[38:41], v16 offset:20480
	ds_read_b128 v[46:49], v16 offset:22528
	ds_read_b128 v[66:69], v13 offset:4096
	ds_read_b128 v[70:73], v13 offset:6144
	v_bfe_u32 v4, v7, 4, 2
	v_bitop3_b32 v14, v4, v17, 4 bitop3:0x36
	v_lshlrev_b32_e32 v15, 4, v14
	v_add_u32_e32 v14, v86, v15
	v_add_u32_e32 v15, v87, v15
	s_waitcnt lgkmcnt(5)
	v_mfma_f32_16x16x32_bf16 v[34:37], v[18:21], v[26:29], 0
	ds_read_b128 v[86:89], v15 offset:16384
	ds_read_b128 v[90:93], v15 offset:18432
	v_add_u32_e32 v17, s80, v106
	v_lshl_add_u64 v[106:107], v[10:11], 0, s[22:23]
	v_mfma_f32_16x16x32_bf16 v[42:45], v[22:25], v[26:29], 0
	v_readfirstlane_b32 s96, v17
	v_lshl_add_u64 v[108:109], v[8:9], 0, s[22:23]
	v_lshl_add_u64 v[110:111], v[10:11], 0, s[24:25]
	s_waitcnt lgkmcnt(5)
	v_mfma_f32_16x16x32_bf16 v[50:53], v[38:41], v[26:29], 0
	s_add_i32 s97, s96, 0x1000
	v_lshl_add_u64 v[112:113], v[8:9], 0, s[24:25]
	s_add_i32 vcc_lo, s96, 0x2000
	s_waitcnt lgkmcnt(4)
	v_mfma_f32_16x16x32_bf16 v[26:29], v[46:49], v[26:29], 0
	v_lshl_add_u64 v[114:115], v[10:11], 0, s[26:27]
	v_lshl_add_u64 v[116:117], v[8:9], 0, s[26:27]
	v_lshl_add_u64 v[118:119], v[10:11], 0, s[30:31]
	v_mfma_f32_16x16x32_bf16 v[54:57], v[18:21], v[30:33], 0
	s_add_i32 vcc_hi, s96, 0x3000
	v_lshl_add_u64 v[120:121], v[8:9], 0, s[30:31]
	v_and_b32_e32 v7, 64, v7
	v_mfma_f32_16x16x32_bf16 v[58:61], v[22:25], v[30:33], 0
	s_add_i32 s15, s82, s83
	v_mfma_f32_16x16x32_bf16 v[62:65], v[38:41], v[30:33], 0
	v_mfma_f32_16x16x32_bf16 v[30:33], v[46:49], v[30:33], 0
	s_waitcnt lgkmcnt(3)
; #define GLDS_STAGE(st, kt_) do { \
;         _Pragma("unroll") for (int i_ = 0; i_ < FI; ++i_) { \
;             glds16(ap + (size_t)(32 * i_) * lda + (kt_) * 64, l3a + (st) + tid * 16 + i_ * 4096); \
;             glds16(bp + (size_t)(32 * i_) * ldb + (kt_) * 64, l3a + (st) + OPB + tid * 16 + i_ * 4096); } } while (0)
; #define GLDS_STAGE(st, kt_) do { \
;         _Pragma("unroll") for (int i_ = 0; i_ < 4; ++i_) { \
;             glds16(ap + (size_t)(64 * i_) * lda + (kt_) * 64, l3a + (st) + tid * 16 + i_ * 8192); \
;             glds16(bp + (size_t)(64 * i_) * ldb + (kt_) * 64, l3a + (st) + 32768 + tid * 16 + i_ * 8192); } } while (0)
; template <int WT, class Epi>
; DEV void gemm_tile(const bf16_t* __restrict__ A, int lda, const bf16_t* __restrict__ Bt, int ldb, int K, unsigned char* lds, const Epi& epi) {
;     ...
;     for (int kt = 0; kt < nk; ++kt) {
;         if (NSTG == 4 && kt + 2 < nk) { if (FI == 2) asm volatile("s_waitcnt vmcnt(8)" ::: "memory"); else asm volatile("s_waitcnt vmcnt(0)" ::: "memory"); }
;         else asm volatile("s_waitcnt vmcnt(0)" ::: "memory");
;         __syncthreads();
;         if (kt + NSTG - 1 < nk) GLDS_STAGE(nxt, kt + NSTG - 1);
; #pragma unroll
;         for (int kh = 0; kh < 2; ++kh) {
;             bf16x8 af[FI], bfr[FI];
;             const int ch = ((kh * 4 + fq) ^ sw) << 4;
; #pragma unroll
;             for (int i = 0; i < FI; ++i) { af[i] = *(const bf16x8*)(lds + cur + aoff + i * 2048 + ch); bfr[i] = *(const bf16x8*)(lds + cur + boff + i * 2048 + ch); }
; #pragma unroll
;             for (int mi = 0; mi < FI; ++mi)
; #pragma unroll
;                 for (int ni = 0; ni < FI; ++ni) acc[mi][ni] = __builtin_amdgcn_mfma_f32_16x16x32_bf16(bfr[ni], af[mi], acc[mi][ni], 0, 0, 0);
;         }
	v_mfma_f32_16x16x32_bf16 v[74:77], v[18:21], v[66:69], 0
	v_mfma_f32_16x16x32_bf16 v[78:81], v[22:25], v[66:69], 0
	v_mfma_f32_16x16x32_bf16 v[82:85], v[38:41], v[66:69], 0
	v_mfma_f32_16x16x32_bf16 v[66:69], v[46:49], v[66:69], 0
	s_waitcnt lgkmcnt(2)
	v_mfma_f32_16x16x32_bf16 v[18:21], v[18:21], v[70:73], 0
	v_mfma_f32_16x16x32_bf16 v[22:25], v[22:25], v[70:73], 0
	v_mfma_f32_16x16x32_bf16 v[38:41], v[38:41], v[70:73], 0
	v_mfma_f32_16x16x32_bf16 v[46:49], v[46:49], v[70:73], 0
	ds_read_b128 v[70:73], v14
	ds_read_b128 v[94:97], v14 offset:2048
	ds_read_b128 v[98:101], v15 offset:20480
	ds_read_b128 v[102:105], v15 offset:22528
	s_waitcnt lgkmcnt(3)
	v_mfma_f32_16x16x32_bf16 v[34:37], v[86:89], v[70:73], v[34:37]
	v_mfma_f32_16x16x32_bf16 v[42:45], v[90:93], v[70:73], v[42:45]
	s_waitcnt lgkmcnt(1)
	v_mfma_f32_16x16x32_bf16 v[50:53], v[98:101], v[70:73], v[50:53]
	s_waitcnt lgkmcnt(0)
	v_mfma_f32_16x16x32_bf16 v[26:29], v[102:105], v[70:73], v[26:29]
	v_mfma_f32_16x16x32_bf16 v[54:57], v[86:89], v[94:97], v[54:57]
	v_mfma_f32_16x16x32_bf16 v[58:61], v[90:93], v[94:97], v[58:61]
	v_mfma_f32_16x16x32_bf16 v[62:65], v[98:101], v[94:97], v[62:65]
	v_mfma_f32_16x16x32_bf16 v[30:33], v[102:105], v[94:97], v[30:33]
	ds_read_b128 v[70:73], v14 offset:4096
	ds_read_b128 v[94:97], v14 offset:6144
	s_waitcnt vmcnt(0)
	s_waitcnt lgkmcnt(0)
	s_barrier
	s_mov_b32 s14, m0
	s_mov_b32 m0, s92
	s_nop 0
	global_load_lds_dwordx4 v[106:107], off
	s_mov_b32 m0, s14
	v_mfma_f32_16x16x32_bf16 v[74:77], v[86:89], v[70:73], v[74:77]
	s_mov_b32 s14, m0
	s_mov_b32 m0, s96
	s_nop 0
	global_load_lds_dwordx4 v[108:109], off
	s_mov_b32 m0, s14
	v_lshl_add_u64 v[106:107], v[10:11], 0, s[34:35]
	s_mov_b32 s14, m0
	s_mov_b32 m0, s95
	s_nop 0
	global_load_lds_dwordx4 v[110:111], off
	s_mov_b32 m0, s14
	v_mfma_f32_16x16x32_bf16 v[78:81], v[90:93], v[70:73], v[78:81]
	s_mov_b32 s14, m0
	s_mov_b32 m0, s97
	s_nop 0
	global_load_lds_dwordx4 v[112:113], off
	s_mov_b32 m0, s14
	v_lshl_add_u64 v[108:109], v[8:9], 0, s[34:35]
	s_mov_b32 s14, m0
	s_mov_b32 m0, s94
	s_nop 0
	global_load_lds_dwordx4 v[114:115], off
	s_mov_b32 m0, s14
	v_mfma_f32_16x16x32_bf16 v[82:85], v[98:101], v[70:73], v[82:85]
	s_mov_b32 s14, m0
	s_mov_b32 m0, vcc_lo
	s_nop 0
	global_load_lds_dwordx4 v[116:117], off
	s_mov_b32 m0, s14
	v_lshl_add_u64 v[110:111], v[10:11], 0, s[36:37]
	s_mov_b32 s14, m0
	s_mov_b32 m0, s93
	s_nop 0
	global_load_lds_dwordx4 v[118:119], off
	s_mov_b32 m0, s14
	v_mfma_f32_16x16x32_bf16 v[66:69], v[102:105], v[70:73], v[66:69]
	s_mov_b32 s14, m0
	s_mov_b32 m0, vcc_hi
	s_nop 0
	global_load_lds_dwordx4 v[120:121], off
	s_mov_b32 m0, s14
	v_lshl_add_u64 v[112:113], v[8:9], 0, s[36:37]
	v_lshl_add_u64 v[114:115], v[10:11], 0, s[38:39]
	v_mfma_f32_16x16x32_bf16 v[18:21], v[86:89], v[94:97], v[18:21]
	ds_read_b128 v[70:73], v16 offset:49152
	ds_read_b128 v[86:89], v16 offset:51200
	v_lshl_add_u64 v[116:117], v[8:9], 0, s[38:39]
	v_lshl_add_u64 v[118:119], v[10:11], 0, s[40:41]
	v_mfma_f32_16x16x32_bf16 v[22:25], v[90:93], v[94:97], v[22:25]
	v_lshl_add_u64 v[120:121], v[8:9], 0, s[40:41]
	v_mfma_f32_16x16x32_bf16 v[38:41], v[98:101], v[94:97], v[38:41]
	v_mfma_f32_16x16x32_bf16 v[46:49], v[102:105], v[94:97], v[46:49]
	ds_read_b128 v[90:93], v13 offset:32768
	ds_read_b128 v[94:97], v13 offset:34816
	ds_read_b128 v[98:101], v16 offset:53248
	ds_read_b128 v[102:105], v16 offset:55296
	s_waitcnt lgkmcnt(3)
	v_mfma_f32_16x16x32_bf16 v[34:37], v[70:73], v[90:93], v[34:37]
	v_mfma_f32_16x16x32_bf16 v[42:45], v[86:89], v[90:93], v[42:45]
	s_waitcnt lgkmcnt(1)
	v_mfma_f32_16x16x32_bf16 v[50:53], v[98:101], v[90:93], v[50:53]
	s_waitcnt lgkmcnt(0)
	v_mfma_f32_16x16x32_bf16 v[26:29], v[102:105], v[90:93], v[26:29]
	v_mfma_f32_16x16x32_bf16 v[54:57], v[70:73], v[94:97], v[54:57]
	v_mfma_f32_16x16x32_bf16 v[58:61], v[86:89], v[94:97], v[58:61]
	v_mfma_f32_16x16x32_bf16 v[62:65], v[98:101], v[94:97], v[62:65]
	v_mfma_f32_16x16x32_bf16 v[30:33], v[102:105], v[94:97], v[30:33]
	ds_read_b128 v[90:93], v13 offset:36864
	ds_read_b128 v[94:97], v13 offset:38912
	s_waitcnt lgkmcnt(1)
	v_mfma_f32_16x16x32_bf16 v[74:77], v[70:73], v[90:93], v[74:77]
	v_mfma_f32_16x16x32_bf16 v[78:81], v[86:89], v[90:93], v[78:81]
	v_mfma_f32_16x16x32_bf16 v[82:85], v[98:101], v[90:93], v[82:85]
	v_mfma_f32_16x16x32_bf16 v[66:69], v[102:105], v[90:93], v[66:69]
	s_waitcnt lgkmcnt(0)
	v_mfma_f32_16x16x32_bf16 v[18:21], v[70:73], v[94:97], v[18:21]
	v_mfma_f32_16x16x32_bf16 v[22:25], v[86:89], v[94:97], v[22:25]
	ds_read_b128 v[70:73], v15 offset:49152
	ds_read_b128 v[86:89], v15 offset:51200
	v_mfma_f32_16x16x32_bf16 v[38:41], v[98:101], v[94:97], v[38:41]
	v_mfma_f32_16x16x32_bf16 v[46:49], v[102:105], v[94:97], v[46:49]
	ds_read_b128 v[90:93], v14 offset:32768
	ds_read_b128 v[94:97], v14 offset:34816
	ds_read_b128 v[98:101], v15 offset:53248
	ds_read_b128 v[102:105], v15 offset:55296
	s_waitcnt lgkmcnt(3)
	v_mfma_f32_16x16x32_bf16 v[34:37], v[70:73], v[90:93], v[34:37]
	v_mfma_f32_16x16x32_bf16 v[42:45], v[86:89], v[90:93], v[42:45]
	s_waitcnt lgkmcnt(1)
	v_mfma_f32_16x16x32_bf16 v[50:53], v[98:101], v[90:93], v[50:53]
	s_waitcnt lgkmcnt(0)
	v_mfma_f32_16x16x32_bf16 v[26:29], v[102:105], v[90:93], v[26:29]
	v_mfma_f32_16x16x32_bf16 v[54:57], v[70:73], v[94:97], v[54:57]
	v_mfma_f32_16x16x32_bf16 v[58:61], v[86:89], v[94:97], v[58:61]
	v_mfma_f32_16x16x32_bf16 v[62:65], v[98:101], v[94:97], v[62:65]
	v_mfma_f32_16x16x32_bf16 v[30:33], v[102:105], v[94:97], v[30:33]
	ds_read_b128 v[90:93], v14 offset:36864
	ds_read_b128 v[94:97], v14 offset:38912
	s_waitcnt vmcnt(0)
	s_waitcnt lgkmcnt(0)
	s_barrier
; #define GLDS_STAGE(st, kt_) do { \
;         _Pragma("unroll") for (int i_ = 0; i_ < FI; ++i_) { \
;             glds16(ap + (size_t)(32 * i_) * lda + (kt_) * 64, l3a + (st) + tid * 16 + i_ * 4096); \
;             glds16(bp + (size_t)(32 * i_) * ldb + (kt_) * 64, l3a + (st) + OPB + tid * 16 + i_ * 4096); } } while (0)
; #define GLDS_STAGE(st, kt_) do { \
;         _Pragma("unroll") for (int i_ = 0; i_ < 4; ++i_) { \
;             glds16(ap + (size_t)(64 * i_) * lda + (kt_) * 64, l3a + (st) + tid * 16 + i_ * 8192); \
;             glds16(bp + (size_t)(64 * i_) * ldb + (kt_) * 64, l3a + (st) + 32768 + tid * 16 + i_ * 8192); } } while (0)
; template <int WT, class Epi>
; DEV void gemm_tile(const bf16_t* __restrict__ A, int lda, const bf16_t* __restrict__ Bt, int ldb, int K, unsigned char* lds, const Epi& epi) {
;     ...
;     for (int kt = 0; kt < nk; ++kt) {
;         if (NSTG == 4 && kt + 2 < nk) { if (FI == 2) asm volatile("s_waitcnt vmcnt(8)" ::: "memory"); else asm volatile("s_waitcnt vmcnt(0)" ::: "memory"); }
;         else asm volatile("s_waitcnt vmcnt(0)" ::: "memory");
;         __syncthreads();
;         if (kt + NSTG - 1 < nk) GLDS_STAGE(nxt, kt + NSTG - 1);
; #pragma unroll
;         for (int kh = 0; kh < 2; ++kh) {
;             bf16x8 af[FI], bfr[FI];
;             const int ch = ((kh * 4 + fq) ^ sw) << 4;
; #pragma unroll
;             for (int i = 0; i < FI; ++i) { af[i] = *(const bf16x8*)(lds + cur + aoff + i * 2048 + ch); bfr[i] = *(const bf16x8*)(lds + cur + boff + i * 2048 + ch); }
; #pragma unroll
;             for (int mi = 0; mi < FI; ++mi)
; #pragma unroll
;                 for (int ni = 0; ni < FI; ++ni) acc[mi][ni] = __builtin_amdgcn_mfma_f32_16x16x32_bf16(bfr[ni], af[mi], acc[mi][ni], 0, 0, 0);
;         }
	s_mov_b32 s14, m0
	s_mov_b32 m0, s78
	s_nop 0
	global_load_lds_dwordx4 v[106:107], off
	s_mov_b32 m0, s14
	v_mfma_f32_16x16x32_bf16 v[74:77], v[70:73], v[90:93], v[74:77]
	s_mov_b32 s14, m0
	s_mov_b32 m0, s88
	s_nop 0
	global_load_lds_dwordx4 v[108:109], off
	s_mov_b32 m0, s14
	v_lshl_add_u64 v[106:107], v[10:11], 0, s[42:43]
	s_mov_b32 s14, m0
	s_mov_b32 m0, s87
	s_nop 0
	global_load_lds_dwordx4 v[110:111], off
	s_mov_b32 m0, s14
	v_mfma_f32_16x16x32_bf16 v[78:81], v[86:89], v[90:93], v[78:81]
	s_mov_b32 s14, m0
	s_mov_b32 m0, s91
	s_nop 0
	global_load_lds_dwordx4 v[112:113], off
	s_mov_b32 m0, s14
	v_lshl_add_u64 v[108:109], v[8:9], 0, s[42:43]
	s_mov_b32 s14, m0
	s_mov_b32 m0, s86
	s_nop 0
	global_load_lds_dwordx4 v[114:115], off
	s_mov_b32 m0, s14
	v_mfma_f32_16x16x32_bf16 v[82:85], v[98:101], v[90:93], v[82:85]
	s_mov_b32 s14, m0
	s_mov_b32 m0, s90
	s_nop 0
	global_load_lds_dwordx4 v[116:117], off
	s_mov_b32 m0, s14
	v_lshl_add_u64 v[110:111], v[10:11], 0, s[44:45]
	s_mov_b32 s14, m0
	s_mov_b32 m0, s79
	s_nop 0
	global_load_lds_dwordx4 v[118:119], off
	s_mov_b32 m0, s14
	v_mfma_f32_16x16x32_bf16 v[66:69], v[102:105], v[90:93], v[66:69]
	s_mov_b32 s14, m0
	s_mov_b32 m0, s89
	s_nop 0
	global_load_lds_dwordx4 v[120:121], off
	s_mov_b32 m0, s14
	v_lshl_add_u64 v[112:113], v[8:9], 0, s[44:45]
	v_lshl_add_u64 v[114:115], v[10:11], 0, s[46:47]
	v_mfma_f32_16x16x32_bf16 v[18:21], v[70:73], v[94:97], v[18:21]
	v_lshl_add_u64 v[116:117], v[8:9], 0, s[46:47]
	v_lshl_add_u64 v[118:119], v[10:11], 0, s[48:49]
	v_lshl_add_u64 v[120:121], v[8:9], 0, s[48:49]
	v_mfma_f32_16x16x32_bf16 v[22:25], v[86:89], v[94:97], v[22:25]
	ds_read_b128 v[70:73], v16 offset:16384
	ds_read_b128 v[86:89], v16 offset:18432
	v_mfma_f32_16x16x32_bf16 v[38:41], v[98:101], v[94:97], v[38:41]
	v_mfma_f32_16x16x32_bf16 v[46:49], v[102:105], v[94:97], v[46:49]
	ds_read_b128 v[90:93], v13
	ds_read_b128 v[94:97], v13 offset:2048
	ds_read_b128 v[98:101], v16 offset:20480
	ds_read_b128 v[102:105], v16 offset:22528
	s_waitcnt lgkmcnt(3)
	v_mfma_f32_16x16x32_bf16 v[34:37], v[70:73], v[90:93], v[34:37]
	v_mfma_f32_16x16x32_bf16 v[42:45], v[86:89], v[90:93], v[42:45]
	s_waitcnt lgkmcnt(1)
	v_mfma_f32_16x16x32_bf16 v[50:53], v[98:101], v[90:93], v[50:53]
	s_waitcnt lgkmcnt(0)
	v_mfma_f32_16x16x32_bf16 v[26:29], v[102:105], v[90:93], v[26:29]
	v_mfma_f32_16x16x32_bf16 v[54:57], v[70:73], v[94:97], v[54:57]
	v_mfma_f32_16x16x32_bf16 v[58:61], v[86:89], v[94:97], v[58:61]
	v_mfma_f32_16x16x32_bf16 v[62:65], v[98:101], v[94:97], v[62:65]
	v_mfma_f32_16x16x32_bf16 v[30:33], v[102:105], v[94:97], v[30:33]
	ds_read_b128 v[90:93], v13 offset:4096
	ds_read_b128 v[94:97], v13 offset:6144
	s_waitcnt lgkmcnt(1)
	v_mfma_f32_16x16x32_bf16 v[74:77], v[70:73], v[90:93], v[74:77]
	v_mfma_f32_16x16x32_bf16 v[78:81], v[86:89], v[90:93], v[78:81]
	v_mfma_f32_16x16x32_bf16 v[82:85], v[98:101], v[90:93], v[82:85]
	v_mfma_f32_16x16x32_bf16 v[66:69], v[102:105], v[90:93], v[66:69]
	s_waitcnt lgkmcnt(0)
	v_mfma_f32_16x16x32_bf16 v[18:21], v[70:73], v[94:97], v[18:21]
	v_mfma_f32_16x16x32_bf16 v[22:25], v[86:89], v[94:97], v[22:25]
	ds_read_b128 v[70:73], v15 offset:16384
	ds_read_b128 v[86:89], v15 offset:18432
	v_mfma_f32_16x16x32_bf16 v[38:41], v[98:101], v[94:97], v[38:41]
	v_mfma_f32_16x16x32_bf16 v[46:49], v[102:105], v[94:97], v[46:49]
	ds_read_b128 v[90:93], v14
	ds_read_b128 v[94:97], v14 offset:2048
	ds_read_b128 v[98:101], v15 offset:20480
	ds_read_b128 v[102:105], v15 offset:22528
	s_waitcnt lgkmcnt(3)
	v_mfma_f32_16x16x32_bf16 v[34:37], v[70:73], v[90:93], v[34:37]
	v_mfma_f32_16x16x32_bf16 v[42:45], v[86:89], v[90:93], v[42:45]
	s_waitcnt lgkmcnt(1)
	v_mfma_f32_16x16x32_bf16 v[50:53], v[98:101], v[90:93], v[50:53]
	s_waitcnt lgkmcnt(0)
	v_mfma_f32_16x16x32_bf16 v[26:29], v[102:105], v[90:93], v[26:29]
	v_mfma_f32_16x16x32_bf16 v[54:57], v[70:73], v[94:97], v[54:57]
	v_mfma_f32_16x16x32_bf16 v[58:61], v[86:89], v[94:97], v[58:61]
	v_mfma_f32_16x16x32_bf16 v[62:65], v[98:101], v[94:97], v[62:65]
	v_mfma_f32_16x16x32_bf16 v[30:33], v[102:105], v[94:97], v[30:33]
	ds_read_b128 v[90:93], v14 offset:4096
	ds_read_b128 v[94:97], v14 offset:6144
	s_waitcnt vmcnt(0)
	s_waitcnt lgkmcnt(0)
	s_barrier
	s_mov_b32 s14, m0
	s_mov_b32 m0, s92
	s_nop 0
	global_load_lds_dwordx4 v[106:107], off
	s_mov_b32 m0, s14
	v_mfma_f32_16x16x32_bf16 v[74:77], v[70:73], v[90:93], v[74:77]
	s_mov_b32 s14, m0
	s_mov_b32 m0, s96
	s_nop 0
	global_load_lds_dwordx4 v[108:109], off
	s_mov_b32 m0, s14
	v_lshl_add_u64 v[106:107], v[10:11], 0, s[50:51]
	s_mov_b32 s14, m0
	s_mov_b32 m0, s95
	s_nop 0
	global_load_lds_dwordx4 v[110:111], off
	s_mov_b32 m0, s14
	v_mfma_f32_16x16x32_bf16 v[78:81], v[86:89], v[90:93], v[78:81]
	s_mov_b32 s14, m0
	s_mov_b32 m0, s97
	s_nop 0
	global_load_lds_dwordx4 v[112:113], off
	s_mov_b32 m0, s14
	v_lshl_add_u64 v[108:109], v[8:9], 0, s[50:51]
	s_mov_b32 s14, m0
	s_mov_b32 m0, s94
	s_nop 0
	global_load_lds_dwordx4 v[114:115], off
	s_mov_b32 m0, s14
	v_mfma_f32_16x16x32_bf16 v[82:85], v[98:101], v[90:93], v[82:85]
	s_mov_b32 s14, m0
	s_mov_b32 m0, vcc_lo
	s_nop 0
	global_load_lds_dwordx4 v[116:117], off
	s_mov_b32 m0, s14
	v_lshl_add_u64 v[110:111], v[10:11], 0, s[52:53]
	s_mov_b32 s14, m0
	s_mov_b32 m0, s93
	s_nop 0
	global_load_lds_dwordx4 v[118:119], off
	s_mov_b32 m0, s14
	v_mfma_f32_16x16x32_bf16 v[66:69], v[102:105], v[90:93], v[66:69]
	s_mov_b32 s14, m0
	s_mov_b32 m0, vcc_hi
	s_nop 0
	global_load_lds_dwordx4 v[120:121], off
	s_mov_b32 m0, s14
	v_lshl_add_u64 v[112:113], v[8:9], 0, s[52:53]
	v_lshl_add_u64 v[114:115], v[10:11], 0, s[54:55]
	v_mfma_f32_16x16x32_bf16 v[18:21], v[70:73], v[94:97], v[18:21]
	v_lshl_add_u64 v[116:117], v[8:9], 0, s[54:55]
	v_lshl_add_u64 v[118:119], v[10:11], 0, s[56:57]
	v_lshl_add_u64 v[120:121], v[8:9], 0, s[56:57]
	v_mfma_f32_16x16x32_bf16 v[22:25], v[86:89], v[94:97], v[22:25]
	ds_read_b128 v[70:73], v16 offset:49152
	ds_read_b128 v[86:89], v16 offset:51200
	v_mfma_f32_16x16x32_bf16 v[38:41], v[98:101], v[94:97], v[38:41]
	v_mfma_f32_16x16x32_bf16 v[46:49], v[102:105], v[94:97], v[46:49]
	ds_read_b128 v[90:93], v13 offset:32768
	ds_read_b128 v[94:97], v13 offset:34816
	ds_read_b128 v[98:101], v16 offset:53248
	ds_read_b128 v[102:105], v16 offset:55296
	s_waitcnt lgkmcnt(3)
; #define GLDS_STAGE(st, kt_) do { \
;         _Pragma("unroll") for (int i_ = 0; i_ < FI; ++i_) { \
;             glds16(ap + (size_t)(32 * i_) * lda + (kt_) * 64, l3a + (st) + tid * 16 + i_ * 4096); \
;             glds16(bp + (size_t)(32 * i_) * ldb + (kt_) * 64, l3a + (st) + OPB + tid * 16 + i_ * 4096); } } while (0)
; #define GLDS_STAGE(st, kt_) do { \
;         _Pragma("unroll") for (int i_ = 0; i_ < 4; ++i_) { \
;             glds16(ap + (size_t)(64 * i_) * lda + (kt_) * 64, l3a + (st) + tid * 16 + i_ * 8192); \
;             glds16(bp + (size_t)(64 * i_) * ldb + (kt_) * 64, l3a + (st) + 32768 + tid * 16 + i_ * 8192); } } while (0)
; template <int WT, class Epi>
; DEV void gemm_tile(const bf16_t* __restrict__ A, int lda, const bf16_t* __restrict__ Bt, int ldb, int K, unsigned char* lds, const Epi& epi) {
;     ...
;     for (int kt = 0; kt < nk; ++kt) {
;         if (NSTG == 4 && kt + 2 < nk) { if (FI == 2) asm volatile("s_waitcnt vmcnt(8)" ::: "memory"); else asm volatile("s_waitcnt vmcnt(0)" ::: "memory"); }
;         else asm volatile("s_waitcnt vmcnt(0)" ::: "memory");
;         __syncthreads();
;         if (kt + NSTG - 1 < nk) GLDS_STAGE(nxt, kt + NSTG - 1);
; #pragma unroll
;         for (int kh = 0; kh < 2; ++kh) {
;             bf16x8 af[FI], bfr[FI];
;             const int ch = ((kh * 4 + fq) ^ sw) << 4;
; #pragma unroll
;             for (int i = 0; i < FI; ++i) { af[i] = *(const bf16x8*)(lds + cur + aoff + i * 2048 + ch); bfr[i] = *(const bf16x8*)(lds + cur + boff + i * 2048 + ch); }
; #pragma unroll
;             for (int mi = 0; mi < FI; ++mi)
; #pragma unroll
;                 for (int ni = 0; ni < FI; ++ni) acc[mi][ni] = __builtin_amdgcn_mfma_f32_16x16x32_bf16(bfr[ni], af[mi], acc[mi][ni], 0, 0, 0);
;         }
	v_mfma_f32_16x16x32_bf16 v[34:37], v[70:73], v[90:93], v[34:37]
	v_mfma_f32_16x16x32_bf16 v[42:45], v[86:89], v[90:93], v[42:45]
	s_waitcnt lgkmcnt(1)
	v_mfma_f32_16x16x32_bf16 v[50:53], v[98:101], v[90:93], v[50:53]
	s_waitcnt lgkmcnt(0)
	v_mfma_f32_16x16x32_bf16 v[26:29], v[102:105], v[90:93], v[26:29]
	v_mfma_f32_16x16x32_bf16 v[54:57], v[70:73], v[94:97], v[54:57]
	v_mfma_f32_16x16x32_bf16 v[58:61], v[86:89], v[94:97], v[58:61]
	v_mfma_f32_16x16x32_bf16 v[62:65], v[98:101], v[94:97], v[62:65]
	v_mfma_f32_16x16x32_bf16 v[30:33], v[102:105], v[94:97], v[30:33]
	ds_read_b128 v[90:93], v13 offset:36864
	ds_read_b128 v[94:97], v13 offset:38912
	s_waitcnt lgkmcnt(1)
	v_mfma_f32_16x16x32_bf16 v[74:77], v[70:73], v[90:93], v[74:77]
	v_mfma_f32_16x16x32_bf16 v[78:81], v[86:89], v[90:93], v[78:81]
	v_mfma_f32_16x16x32_bf16 v[82:85], v[98:101], v[90:93], v[82:85]
	v_mfma_f32_16x16x32_bf16 v[66:69], v[102:105], v[90:93], v[66:69]
	s_waitcnt lgkmcnt(0)
	v_mfma_f32_16x16x32_bf16 v[18:21], v[70:73], v[94:97], v[18:21]
	v_mfma_f32_16x16x32_bf16 v[22:25], v[86:89], v[94:97], v[22:25]
	ds_read_b128 v[70:73], v15 offset:49152
	ds_read_b128 v[86:89], v15 offset:51200
	v_mfma_f32_16x16x32_bf16 v[38:41], v[98:101], v[94:97], v[38:41]
	v_mfma_f32_16x16x32_bf16 v[46:49], v[102:105], v[94:97], v[46:49]
	ds_read_b128 v[90:93], v14 offset:32768
	ds_read_b128 v[94:97], v14 offset:34816
	ds_read_b128 v[98:101], v15 offset:53248
	ds_read_b128 v[102:105], v15 offset:55296
	s_waitcnt lgkmcnt(3)
	v_mfma_f32_16x16x32_bf16 v[34:37], v[70:73], v[90:93], v[34:37]
	v_mfma_f32_16x16x32_bf16 v[42:45], v[86:89], v[90:93], v[42:45]
	s_waitcnt lgkmcnt(1)
	v_mfma_f32_16x16x32_bf16 v[50:53], v[98:101], v[90:93], v[50:53]
	s_waitcnt lgkmcnt(0)
	v_mfma_f32_16x16x32_bf16 v[26:29], v[102:105], v[90:93], v[26:29]
	v_mfma_f32_16x16x32_bf16 v[54:57], v[70:73], v[94:97], v[54:57]
	v_mfma_f32_16x16x32_bf16 v[58:61], v[86:89], v[94:97], v[58:61]
	v_mfma_f32_16x16x32_bf16 v[62:65], v[98:101], v[94:97], v[62:65]
	v_mfma_f32_16x16x32_bf16 v[30:33], v[102:105], v[94:97], v[30:33]
	ds_read_b128 v[90:93], v14 offset:36864
	ds_read_b128 v[94:97], v14 offset:38912
	s_waitcnt vmcnt(0)
	s_waitcnt lgkmcnt(0)
	s_barrier
	s_mov_b32 s14, m0
	s_mov_b32 m0, s78
	s_nop 0
	global_load_lds_dwordx4 v[106:107], off
	s_mov_b32 m0, s14
	v_mfma_f32_16x16x32_bf16 v[74:77], v[70:73], v[90:93], v[74:77]
	s_mov_b32 s14, m0
	s_mov_b32 m0, s88
	s_nop 0
	global_load_lds_dwordx4 v[108:109], off
	s_mov_b32 m0, s14
	v_lshl_add_u64 v[106:107], v[10:11], 0, s[58:59]
	s_mov_b32 s14, m0
	s_mov_b32 m0, s87
	s_nop 0
	global_load_lds_dwordx4 v[110:111], off
	s_mov_b32 m0, s14
	v_mfma_f32_16x16x32_bf16 v[78:81], v[86:89], v[90:93], v[78:81]
	s_mov_b32 s14, m0
	s_mov_b32 m0, s91
	s_nop 0
	global_load_lds_dwordx4 v[112:113], off
	s_mov_b32 m0, s14
	v_lshl_add_u64 v[108:109], v[8:9], 0, s[58:59]
	s_mov_b32 s14, m0
	s_mov_b32 m0, s86
	s_nop 0
	global_load_lds_dwordx4 v[114:115], off
	s_mov_b32 m0, s14
	v_mfma_f32_16x16x32_bf16 v[82:85], v[98:101], v[90:93], v[82:85]
	s_mov_b32 s14, m0
	s_mov_b32 m0, s90
	s_nop 0
	global_load_lds_dwordx4 v[116:117], off
	s_mov_b32 m0, s14
	v_lshl_add_u64 v[110:111], v[10:11], 0, s[60:61]
	s_mov_b32 s14, m0
	s_mov_b32 m0, s79
	s_nop 0
	global_load_lds_dwordx4 v[118:119], off
	s_mov_b32 m0, s14
	v_mfma_f32_16x16x32_bf16 v[66:69], v[102:105], v[90:93], v[66:69]
	s_mov_b32 s14, m0
	s_mov_b32 m0, s89
	s_nop 0
	global_load_lds_dwordx4 v[120:121], off
	s_mov_b32 m0, s14
	v_lshl_add_u64 v[112:113], v[8:9], 0, s[60:61]
	v_lshl_add_u64 v[114:115], v[10:11], 0, s[62:63]
	v_mfma_f32_16x16x32_bf16 v[18:21], v[70:73], v[94:97], v[18:21]
	v_lshl_add_u64 v[116:117], v[8:9], 0, s[62:63]
	v_lshl_add_u64 v[118:119], v[10:11], 0, s[64:65]
	v_lshl_add_u64 v[120:121], v[8:9], 0, s[64:65]
	v_mfma_f32_16x16x32_bf16 v[22:25], v[86:89], v[94:97], v[22:25]
	ds_read_b128 v[70:73], v16 offset:16384
	ds_read_b128 v[86:89], v16 offset:18432
	v_mfma_f32_16x16x32_bf16 v[38:41], v[98:101], v[94:97], v[38:41]
	v_mfma_f32_16x16x32_bf16 v[46:49], v[102:105], v[94:97], v[46:49]
	ds_read_b128 v[90:93], v13
	ds_read_b128 v[94:97], v13 offset:2048
	ds_read_b128 v[98:101], v16 offset:20480
	ds_read_b128 v[102:105], v16 offset:22528
	s_waitcnt lgkmcnt(3)
	v_mfma_f32_16x16x32_bf16 v[34:37], v[70:73], v[90:93], v[34:37]
	v_mfma_f32_16x16x32_bf16 v[42:45], v[86:89], v[90:93], v[42:45]
	s_waitcnt lgkmcnt(1)
	v_mfma_f32_16x16x32_bf16 v[50:53], v[98:101], v[90:93], v[50:53]
	s_waitcnt lgkmcnt(0)
	v_mfma_f32_16x16x32_bf16 v[26:29], v[102:105], v[90:93], v[26:29]
	v_mfma_f32_16x16x32_bf16 v[54:57], v[70:73], v[94:97], v[54:57]
	v_mfma_f32_16x16x32_bf16 v[58:61], v[86:89], v[94:97], v[58:61]
	v_mfma_f32_16x16x32_bf16 v[62:65], v[98:101], v[94:97], v[62:65]
	v_mfma_f32_16x16x32_bf16 v[30:33], v[102:105], v[94:97], v[30:33]
	ds_read_b128 v[90:93], v13 offset:4096
	ds_read_b128 v[94:97], v13 offset:6144
	s_waitcnt lgkmcnt(1)
	v_mfma_f32_16x16x32_bf16 v[74:77], v[70:73], v[90:93], v[74:77]
	v_mfma_f32_16x16x32_bf16 v[78:81], v[86:89], v[90:93], v[78:81]
	v_mfma_f32_16x16x32_bf16 v[82:85], v[98:101], v[90:93], v[82:85]
	v_mfma_f32_16x16x32_bf16 v[66:69], v[102:105], v[90:93], v[66:69]
	s_waitcnt lgkmcnt(0)
	v_mfma_f32_16x16x32_bf16 v[18:21], v[70:73], v[94:97], v[18:21]
	v_mfma_f32_16x16x32_bf16 v[22:25], v[86:89], v[94:97], v[22:25]
	ds_read_b128 v[70:73], v15 offset:16384
	ds_read_b128 v[86:89], v15 offset:18432
	v_mfma_f32_16x16x32_bf16 v[38:41], v[98:101], v[94:97], v[38:41]
	v_mfma_f32_16x16x32_bf16 v[46:49], v[102:105], v[94:97], v[46:49]
	ds_read_b128 v[90:93], v14
	ds_read_b128 v[94:97], v14 offset:2048
	ds_read_b128 v[98:101], v15 offset:20480
	ds_read_b128 v[102:105], v15 offset:22528
	s_waitcnt lgkmcnt(3)
	v_mfma_f32_16x16x32_bf16 v[34:37], v[70:73], v[90:93], v[34:37]
	v_mfma_f32_16x16x32_bf16 v[42:45], v[86:89], v[90:93], v[42:45]
	s_waitcnt lgkmcnt(1)
	v_mfma_f32_16x16x32_bf16 v[50:53], v[98:101], v[90:93], v[50:53]
	s_waitcnt lgkmcnt(0)
	v_mfma_f32_16x16x32_bf16 v[26:29], v[102:105], v[90:93], v[26:29]
	v_mfma_f32_16x16x32_bf16 v[54:57], v[70:73], v[94:97], v[54:57]
	v_mfma_f32_16x16x32_bf16 v[58:61], v[86:89], v[94:97], v[58:61]
	v_mfma_f32_16x16x32_bf16 v[62:65], v[98:101], v[94:97], v[62:65]
	v_mfma_f32_16x16x32_bf16 v[30:33], v[102:105], v[94:97], v[30:33]
	ds_read_b128 v[90:93], v14 offset:4096
	ds_read_b128 v[94:97], v14 offset:6144
	s_waitcnt vmcnt(0)
	s_waitcnt lgkmcnt(0)
	s_barrier
; #define GLDS_STAGE(st, kt_) do { \
;         _Pragma("unroll") for (int i_ = 0; i_ < FI; ++i_) { \
;             glds16(ap + (size_t)(32 * i_) * lda + (kt_) * 64, l3a + (st) + tid * 16 + i_ * 4096); \
;             glds16(bp + (size_t)(32 * i_) * ldb + (kt_) * 64, l3a + (st) + OPB + tid * 16 + i_ * 4096); } } while (0)
; #define GLDS_STAGE(st, kt_) do { \
;         _Pragma("unroll") for (int i_ = 0; i_ < 4; ++i_) { \
;             glds16(ap + (size_t)(64 * i_) * lda + (kt_) * 64, l3a + (st) + tid * 16 + i_ * 8192); \
;             glds16(bp + (size_t)(64 * i_) * ldb + (kt_) * 64, l3a + (st) + 32768 + tid * 16 + i_ * 8192); } } while (0)
; template <int WT, class Epi>
; DEV void gemm_tile(const bf16_t* __restrict__ A, int lda, const bf16_t* __restrict__ Bt, int ldb, int K, unsigned char* lds, const Epi& epi) {
;     ...
;     for (int kt = 0; kt < nk; ++kt) {
;         if (NSTG == 4 && kt + 2 < nk) { if (FI == 2) asm volatile("s_waitcnt vmcnt(8)" ::: "memory"); else asm volatile("s_waitcnt vmcnt(0)" ::: "memory"); }
;         else asm volatile("s_waitcnt vmcnt(0)" ::: "memory");
;         __syncthreads();
;         if (kt + NSTG - 1 < nk) GLDS_STAGE(nxt, kt + NSTG - 1);
; #pragma unroll
;         for (int kh = 0; kh < 2; ++kh) {
;             bf16x8 af[FI], bfr[FI];
;             const int ch = ((kh * 4 + fq) ^ sw) << 4;
; #pragma unroll
;             for (int i = 0; i < FI; ++i) { af[i] = *(const bf16x8*)(lds + cur + aoff + i * 2048 + ch); bfr[i] = *(const bf16x8*)(lds + cur + boff + i * 2048 + ch); }
; #pragma unroll
;             for (int mi = 0; mi < FI; ++mi)
; #pragma unroll
;                 for (int ni = 0; ni < FI; ++ni) acc[mi][ni] = __builtin_amdgcn_mfma_f32_16x16x32_bf16(bfr[ni], af[mi], acc[mi][ni], 0, 0, 0);
;         }
	s_mov_b32 s14, m0
	s_mov_b32 m0, s92
	s_nop 0
	global_load_lds_dwordx4 v[106:107], off
	s_mov_b32 m0, s14
	v_mfma_f32_16x16x32_bf16 v[74:77], v[70:73], v[90:93], v[74:77]
	s_mov_b32 s14, m0
	s_mov_b32 m0, s96
	s_nop 0
	global_load_lds_dwordx4 v[108:109], off
	s_mov_b32 m0, s14
	v_lshl_add_u64 v[106:107], v[10:11], 0, s[66:67]
	s_mov_b32 s14, m0
	s_mov_b32 m0, s95
	s_nop 0
	global_load_lds_dwordx4 v[110:111], off
	s_mov_b32 m0, s14
	v_mfma_f32_16x16x32_bf16 v[78:81], v[86:89], v[90:93], v[78:81]
	s_mov_b32 s14, m0
	s_mov_b32 m0, s97
	s_nop 0
	global_load_lds_dwordx4 v[112:113], off
	s_mov_b32 m0, s14
	v_lshl_add_u64 v[108:109], v[8:9], 0, s[66:67]
	s_mov_b32 s14, m0
	s_mov_b32 m0, s94
	s_nop 0
	global_load_lds_dwordx4 v[114:115], off
	s_mov_b32 m0, s14
	v_mfma_f32_16x16x32_bf16 v[82:85], v[98:101], v[90:93], v[82:85]
	s_mov_b32 s14, m0
	s_mov_b32 m0, vcc_lo
	s_nop 0
	global_load_lds_dwordx4 v[116:117], off
	s_mov_b32 m0, s14
	v_lshl_add_u64 v[110:111], v[10:11], 0, s[68:69]
	s_mov_b32 s14, m0
	s_mov_b32 m0, s93
	s_nop 0
	global_load_lds_dwordx4 v[118:119], off
	s_mov_b32 m0, s14
	v_mfma_f32_16x16x32_bf16 v[66:69], v[102:105], v[90:93], v[66:69]
	s_mov_b32 s14, m0
	s_mov_b32 m0, vcc_hi
	s_nop 0
	global_load_lds_dwordx4 v[120:121], off
	s_mov_b32 m0, s14
	v_lshl_add_u64 v[112:113], v[8:9], 0, s[68:69]
	v_lshl_add_u64 v[114:115], v[10:11], 0, s[70:71]
	v_mfma_f32_16x16x32_bf16 v[18:21], v[70:73], v[94:97], v[18:21]
	v_lshl_add_u64 v[116:117], v[8:9], 0, s[70:71]
	v_lshl_add_u64 v[118:119], v[10:11], 0, s[72:73]
	v_lshl_add_u64 v[120:121], v[8:9], 0, s[72:73]
	v_mfma_f32_16x16x32_bf16 v[22:25], v[86:89], v[94:97], v[22:25]
	ds_read_b128 v[70:73], v16 offset:49152
	ds_read_b128 v[86:89], v16 offset:51200
	v_mfma_f32_16x16x32_bf16 v[38:41], v[98:101], v[94:97], v[38:41]
	v_mfma_f32_16x16x32_bf16 v[46:49], v[102:105], v[94:97], v[46:49]
	ds_read_b128 v[90:93], v13 offset:32768
	ds_read_b128 v[94:97], v13 offset:34816
	ds_read_b128 v[98:101], v16 offset:53248
	ds_read_b128 v[102:105], v16 offset:55296
	s_waitcnt lgkmcnt(3)
	v_mfma_f32_16x16x32_bf16 v[34:37], v[70:73], v[90:93], v[34:37]
	v_mfma_f32_16x16x32_bf16 v[42:45], v[86:89], v[90:93], v[42:45]
	s_waitcnt lgkmcnt(1)
	v_mfma_f32_16x16x32_bf16 v[50:53], v[98:101], v[90:93], v[50:53]
	s_waitcnt lgkmcnt(0)
	v_mfma_f32_16x16x32_bf16 v[26:29], v[102:105], v[90:93], v[26:29]
	v_mfma_f32_16x16x32_bf16 v[54:57], v[70:73], v[94:97], v[54:57]
	v_mfma_f32_16x16x32_bf16 v[58:61], v[86:89], v[94:97], v[58:61]
	v_mfma_f32_16x16x32_bf16 v[62:65], v[98:101], v[94:97], v[62:65]
	v_mfma_f32_16x16x32_bf16 v[30:33], v[102:105], v[94:97], v[30:33]
	ds_read_b128 v[90:93], v13 offset:36864
	ds_read_b128 v[94:97], v13 offset:38912
	s_waitcnt lgkmcnt(1)
	v_mfma_f32_16x16x32_bf16 v[74:77], v[70:73], v[90:93], v[74:77]
	v_mfma_f32_16x16x32_bf16 v[78:81], v[86:89], v[90:93], v[78:81]
	v_mfma_f32_16x16x32_bf16 v[82:85], v[98:101], v[90:93], v[82:85]
	v_mfma_f32_16x16x32_bf16 v[66:69], v[102:105], v[90:93], v[66:69]
	s_waitcnt lgkmcnt(0)
	v_mfma_f32_16x16x32_bf16 v[18:21], v[70:73], v[94:97], v[18:21]
	v_mfma_f32_16x16x32_bf16 v[22:25], v[86:89], v[94:97], v[22:25]
	ds_read_b128 v[70:73], v15 offset:49152
	ds_read_b128 v[86:89], v15 offset:51200
	v_mfma_f32_16x16x32_bf16 v[38:41], v[98:101], v[94:97], v[38:41]
	v_mfma_f32_16x16x32_bf16 v[46:49], v[102:105], v[94:97], v[46:49]
	ds_read_b128 v[90:93], v14 offset:32768
	ds_read_b128 v[94:97], v14 offset:34816
	ds_read_b128 v[98:101], v15 offset:53248
	ds_read_b128 v[102:105], v15 offset:55296
	s_waitcnt lgkmcnt(3)
	v_mfma_f32_16x16x32_bf16 v[34:37], v[70:73], v[90:93], v[34:37]
	v_mfma_f32_16x16x32_bf16 v[42:45], v[86:89], v[90:93], v[42:45]
	s_waitcnt lgkmcnt(1)
	v_mfma_f32_16x16x32_bf16 v[50:53], v[98:101], v[90:93], v[50:53]
	s_waitcnt lgkmcnt(0)
	v_mfma_f32_16x16x32_bf16 v[26:29], v[102:105], v[90:93], v[26:29]
	v_mfma_f32_16x16x32_bf16 v[54:57], v[70:73], v[94:97], v[54:57]
	v_mfma_f32_16x16x32_bf16 v[58:61], v[86:89], v[94:97], v[58:61]
	v_mfma_f32_16x16x32_bf16 v[62:65], v[98:101], v[94:97], v[62:65]
	v_mfma_f32_16x16x32_bf16 v[30:33], v[102:105], v[94:97], v[30:33]
	ds_read_b128 v[90:93], v14 offset:36864
	ds_read_b128 v[94:97], v14 offset:38912
	s_waitcnt vmcnt(0)
	s_waitcnt lgkmcnt(0)
	s_barrier
; #define GLDS_STAGE(st, kt_) do { \
;         _Pragma("unroll") for (int i_ = 0; i_ < FI; ++i_) { \
;             glds16(ap + (size_t)(32 * i_) * lda + (kt_) * 64, l3a + (st) + tid * 16 + i_ * 4096); \
;             glds16(bp + (size_t)(32 * i_) * ldb + (kt_) * 64, l3a + (st) + OPB + tid * 16 + i_ * 4096); } } while (0)
; #define GLDS_STAGE(st, kt_) do { \
;         _Pragma("unroll") for (int i_ = 0; i_ < 4; ++i_) { \
;             glds16(ap + (size_t)(64 * i_) * lda + (kt_) * 64, l3a + (st) + tid * 16 + i_ * 8192); \
;             glds16(bp + (size_t)(64 * i_) * ldb + (kt_) * 64, l3a + (st) + 32768 + tid * 16 + i_ * 8192); } } while (0)
; #define VLOOP(t, N) for (int t##0_ = 2 * bid, t = min(t##0_ + vb, (N) - 1); t##0_ < (N); t##0_ += VG, t = min(t##0_ + vb, (N) - 1))
; template <int WT, class Epi>
; DEV void gemm_tile(const bf16_t* __restrict__ A, int lda, const bf16_t* __restrict__ Bt, int ldb, int K, unsigned char* lds, const Epi& epi) {
;     ...
;     for (int kt = 0; kt < nk; ++kt) {
;         if (NSTG == 4 && kt + 2 < nk) { if (FI == 2) asm volatile("s_waitcnt vmcnt(8)" ::: "memory"); else asm volatile("s_waitcnt vmcnt(0)" ::: "memory"); }
;         else asm volatile("s_waitcnt vmcnt(0)" ::: "memory");
;         __syncthreads();
;         if (kt + NSTG - 1 < nk) GLDS_STAGE(nxt, kt + NSTG - 1);
; #pragma unroll
;         for (int kh = 0; kh < 2; ++kh) {
;             bf16x8 af[FI], bfr[FI];
;             const int ch = ((kh * 4 + fq) ^ sw) << 4;
; #pragma unroll
;             for (int i = 0; i < FI; ++i) { af[i] = *(const bf16x8*)(lds + cur + aoff + i * 2048 + ch); bfr[i] = *(const bf16x8*)(lds + cur + boff + i * 2048 + ch); }
; #pragma unroll
;             for (int mi = 0; mi < FI; ++mi)
; #pragma unroll
;                 for (int ni = 0; ni < FI; ++ni) acc[mi][ni] = __builtin_amdgcn_mfma_f32_16x16x32_bf16(bfr[ni], af[mi], acc[mi][ni], 0, 0, 0);
;         }
;         nxt = cur; cur += STB; if (cur == NSTG * STB) cur = 0;
;     }
; __global__ void __launch_bounds__(512) hymba_fwd(Params p) {
;     ...
;         VLOOP(t, NS1) { const int bhd = t >> 5, v = t & 31, mt = v >> 1, nt = v & 1, b = bhd >> 2, hd = bhd & 3;
	s_mov_b32 s14, m0
	s_mov_b32 m0, s78
	s_nop 0
	global_load_lds_dwordx4 v[106:107], off
	s_mov_b32 m0, s14
	v_mfma_f32_16x16x32_bf16 v[74:77], v[70:73], v[90:93], v[74:77]
	s_mov_b32 s14, m0
	s_mov_b32 m0, s88
	s_nop 0
	global_load_lds_dwordx4 v[108:109], off
	s_mov_b32 m0, s14
	s_lshl_b32 s78, s77, 2
	s_mov_b32 s14, m0
	s_mov_b32 m0, s87
	s_nop 0
	global_load_lds_dwordx4 v[110:111], off
	s_mov_b32 m0, s14
	v_mfma_f32_16x16x32_bf16 v[78:81], v[86:89], v[90:93], v[78:81]
	s_mov_b32 s14, m0
	s_mov_b32 m0, s91
	s_nop 0
	global_load_lds_dwordx4 v[112:113], off
	s_mov_b32 m0, s14
	s_ashr_i32 s77, s76, 31
	s_mov_b32 s14, m0
	s_mov_b32 m0, s86
	s_nop 0
	global_load_lds_dwordx4 v[114:115], off
	s_mov_b32 m0, s14
	v_mfma_f32_16x16x32_bf16 v[8:11], v[98:101], v[90:93], v[82:85]
	s_mov_b32 s14, m0
	s_mov_b32 m0, s90
	s_nop 0
	global_load_lds_dwordx4 v[116:117], off
	s_mov_b32 m0, s14
	s_lshl_b64 s[76:77], s[76:77], 12
	s_mov_b32 s14, m0
	s_mov_b32 m0, s79
	s_nop 0
	global_load_lds_dwordx4 v[118:119], off
	s_mov_b32 m0, s14
	v_mfma_f32_16x16x32_bf16 v[66:69], v[102:105], v[90:93], v[66:69]
	s_mov_b32 s14, m0
	s_mov_b32 m0, s89
	s_nop 0
	global_load_lds_dwordx4 v[120:121], off
	s_mov_b32 m0, s14
	s_mov_b32 s79, s5
	s_add_i32 s14, s83, s75
	v_mfma_f32_16x16x32_bf16 v[18:21], v[70:73], v[94:97], v[18:21]
	ds_read_b128 v[70:73], v16 offset:16384
	ds_read_b128 v[82:85], v16 offset:18432
	s_min_i32 s86, s15, 0x1ff
	s_mov_b32 s83, s14
	v_mfma_f32_16x16x32_bf16 v[22:25], v[86:89], v[94:97], v[22:25]
	ds_read_b128 v[86:89], v13
	ds_read_b128 v[90:93], v13 offset:2048
	s_cmpk_lt_i32 s14, 0x200
	v_mfma_f32_16x16x32_bf16 v[38:41], v[98:101], v[94:97], v[38:41]
	ds_read_b128 v[98:101], v16 offset:22528
	v_mfma_f32_16x16x32_bf16 v[46:49], v[102:105], v[94:97], v[46:49]
	ds_read_b128 v[94:97], v16 offset:20480
	v_or_b32_e32 v102, 48, v6
	v_lshl_add_u64 v[104:105], v[2:3], 0, s[76:77]
	s_waitcnt lgkmcnt(3)
	v_mfma_f32_16x16x32_bf16 v[34:37], v[70:73], v[86:89], v[34:37]
	v_ashrrev_i32_e32 v103, 31, v102
	v_mfma_f32_16x16x32_bf16 v[42:45], v[82:85], v[86:89], v[42:45]
	s_waitcnt lgkmcnt(0)
	v_mfma_f32_16x16x32_bf16 v[50:53], v[94:97], v[86:89], v[50:53]
	v_mfma_f32_16x16x32_bf16 v[26:29], v[98:101], v[86:89], v[26:29]
	v_mfma_f32_16x16x32_bf16 v[54:57], v[70:73], v[90:93], v[54:57]
	v_mfma_f32_16x16x32_bf16 v[58:61], v[82:85], v[90:93], v[58:61]
	v_mfma_f32_16x16x32_bf16 v[62:65], v[94:97], v[90:93], v[62:65]
	v_mfma_f32_16x16x32_bf16 v[30:33], v[98:101], v[90:93], v[30:33]
	ds_read_b128 v[86:89], v13 offset:4096
	ds_read_b128 v[90:93], v13 offset:6144
	s_waitcnt lgkmcnt(1)
	v_mfma_f32_16x16x32_bf16 v[74:77], v[70:73], v[86:89], v[74:77]
	v_mfma_f32_16x16x32_bf16 v[78:81], v[82:85], v[86:89], v[78:81]
	v_mfma_f32_16x16x32_bf16 v[8:11], v[94:97], v[86:89], v[8:11]
	v_mfma_f32_16x16x32_bf16 v[66:69], v[98:101], v[86:89], v[66:69]
	s_waitcnt lgkmcnt(0)
	v_mfma_f32_16x16x32_bf16 v[18:21], v[70:73], v[90:93], v[18:21]
	v_mfma_f32_16x16x32_bf16 v[22:25], v[82:85], v[90:93], v[22:25]
	ds_read_b128 v[70:73], v15 offset:16384
	ds_read_b128 v[82:85], v15 offset:18432
	v_mfma_f32_16x16x32_bf16 v[38:41], v[94:97], v[90:93], v[38:41]
	v_mfma_f32_16x16x32_bf16 v[46:49], v[98:101], v[90:93], v[46:49]
	ds_read_b128 v[86:89], v14
	ds_read_b128 v[90:93], v14 offset:2048
	ds_read_b128 v[94:97], v15 offset:20480
	ds_read_b128 v[98:101], v15 offset:22528
	s_waitcnt lgkmcnt(3)
	v_mfma_f32_16x16x32_bf16 v[34:37], v[70:73], v[86:89], v[34:37]
	v_mfma_f32_16x16x32_bf16 v[42:45], v[82:85], v[86:89], v[42:45]
	s_waitcnt lgkmcnt(1)
	v_mfma_f32_16x16x32_bf16 v[50:53], v[94:97], v[86:89], v[50:53]
	s_waitcnt lgkmcnt(0)
	v_mfma_f32_16x16x32_bf16 v[26:29], v[98:101], v[86:89], v[26:29]
	v_mfma_f32_16x16x32_bf16 v[54:57], v[70:73], v[90:93], v[54:57]
	v_mfma_f32_16x16x32_bf16 v[58:61], v[82:85], v[90:93], v[58:61]
	v_mfma_f32_16x16x32_bf16 v[62:65], v[94:97], v[90:93], v[62:65]
	v_mfma_f32_16x16x32_bf16 v[30:33], v[98:101], v[90:93], v[30:33]
	ds_read_b128 v[86:89], v14 offset:4096
	ds_read_b128 v[90:93], v14 offset:6144
	s_waitcnt vmcnt(0)
	s_waitcnt lgkmcnt(0)
	v_mfma_f32_16x16x32_bf16 v[74:77], v[70:73], v[86:89], v[74:77]
	s_barrier
	v_mfma_f32_16x16x32_bf16 v[78:81], v[82:85], v[86:89], v[78:81]
	v_mfma_f32_16x16x32_bf16 v[8:11], v[94:97], v[86:89], v[8:11]
	v_mfma_f32_16x16x32_bf16 v[66:69], v[98:101], v[86:89], v[66:69]
	ds_read_b128 v[86:89], v16 offset:51200
	v_mfma_f32_16x16x32_bf16 v[18:21], v[70:73], v[90:93], v[18:21]
	ds_read_b128 v[70:73], v16 offset:49152
	v_mfma_f32_16x16x32_bf16 v[22:25], v[82:85], v[90:93], v[22:25]
	ds_read_b128 v[82:85], v13 offset:32768
	v_mfma_f32_16x16x32_bf16 v[38:41], v[94:97], v[90:93], v[38:41]
	ds_read_b128 v[94:97], v16 offset:55296
	v_mfma_f32_16x16x32_bf16 v[46:49], v[98:101], v[90:93], v[46:49]
	ds_read_b128 v[90:93], v16 offset:53248
	v_or_b32_e32 v98, 16, v6
	v_or_b32_e32 v100, 32, v6
	s_waitcnt lgkmcnt(2)
	v_mfma_f32_16x16x32_bf16 v[34:37], v[70:73], v[82:85], v[34:37]
	v_ashrrev_i32_e32 v99, 31, v98
	v_ashrrev_i32_e32 v101, 31, v100
	v_mfma_f32_16x16x32_bf16 v[42:45], v[86:89], v[82:85], v[42:45]
	s_waitcnt lgkmcnt(0)
	v_mfma_f32_16x16x32_bf16 v[50:53], v[90:93], v[82:85], v[50:53]
	v_mfma_f32_16x16x32_bf16 v[26:29], v[94:97], v[82:85], v[26:29]
	ds_read_b128 v[82:85], v13 offset:34816
	s_waitcnt lgkmcnt(0)
	v_mfma_f32_16x16x32_bf16 v[54:57], v[70:73], v[82:85], v[54:57]
	v_mfma_f32_16x16x32_bf16 v[58:61], v[86:89], v[82:85], v[58:61]
	v_mfma_f32_16x16x32_bf16 v[62:65], v[90:93], v[82:85], v[62:65]
	v_mfma_f32_16x16x32_bf16 v[30:33], v[94:97], v[82:85], v[30:33]
	ds_read_b128 v[82:85], v13 offset:36864
	s_waitcnt lgkmcnt(0)
; template <int WT, class Epi>
; DEV void gemm_tile(const bf16_t* __restrict__ A, int lda, const bf16_t* __restrict__ Bt, int ldb, int K, unsigned char* lds, const Epi& epi) {
;     ...
; #pragma unroll
;         for (int mi = 0; mi < FI; ++mi)
; #pragma unroll
;             for (int ni = 0; ni < FI; ++ni) epi(wr * WT + mi * 16 + fr, wc * WT + ni * 16 + fq * 4, acc[mi][ni]);
	v_mfma_f32_16x16x32_bf16 v[74:77], v[70:73], v[82:85], v[74:77]
	v_mfma_f32_16x16x32_bf16 v[78:81], v[86:89], v[82:85], v[78:81]
	v_mfma_f32_16x16x32_bf16 v[8:11], v[90:93], v[82:85], v[8:11]
	v_mfma_f32_16x16x32_bf16 v[66:69], v[94:97], v[82:85], v[66:69]
	ds_read_b128 v[82:85], v13 offset:38912
	v_lshlrev_b32_e32 v13, 2, v7
	v_ashrrev_i32_e32 v7, 31, v6
	s_waitcnt lgkmcnt(0)
	v_mfma_f32_16x16x32_bf16 v[16:19], v[70:73], v[82:85], v[18:21]
	ds_read_b128 v[70:73], v15 offset:49152
	v_lshlrev_b64 v[106:107], 12, v[6:7]
	v_lshl_add_u64 v[6:7], v[104:105], 0, s[4:5]
	v_mfma_f32_16x16x32_bf16 v[20:23], v[86:89], v[82:85], v[22:25]
	ds_read_b128 v[86:89], v15 offset:51200
	v_lshl_or_b32 v4, v4, 4, v13
	v_mfma_f32_16x16x32_bf16 v[38:41], v[90:93], v[82:85], v[38:41]
	ds_read_b128 v[90:93], v15 offset:53248
	v_mfma_f32_16x16x32_bf16 v[46:49], v[94:97], v[82:85], v[46:49]
	ds_read_b128 v[94:97], v15 offset:55296
	ds_read_b128 v[82:85], v14 offset:32768
	s_waitcnt lgkmcnt(0)
	v_mfma_f32_16x16x32_bf16 v[34:37], v[70:73], v[82:85], v[34:37]
	v_mfma_f32_16x16x32_bf16 v[42:45], v[86:89], v[82:85], v[42:45]
	s_nop 6
	v_mul_f32_e64 v36, v36, s74
	v_mul_f32_e64 v37, v37, s74
	v_pk_mul_f32 v[34:35], v[34:35], s[74:75] op_sel_hi:[1,0]
	v_mfma_f32_16x16x32_bf16 v[50:53], v[90:93], v[82:85], v[50:53]
	v_mfma_f32_16x16x32_bf16 v[24:27], v[94:97], v[82:85], v[26:29]
	ds_read_b128 v[82:85], v14 offset:34816
	v_pk_mul_f32 v[44:45], v[44:45], s[74:75] op_sel_hi:[1,0]
	v_pk_mul_f32 v[42:43], v[42:43], s[74:75] op_sel_hi:[1,0]
	s_waitcnt lgkmcnt(0)
	v_mfma_f32_16x16x32_bf16 v[54:57], v[70:73], v[82:85], v[54:57]
	s_nop 1
	v_mul_f32_e64 v52, v52, s74
	v_mul_f32_e64 v53, v53, s74
	v_pk_mul_f32 v[50:51], v[50:51], s[74:75] op_sel_hi:[1,0]
	v_pk_mul_f32 v[26:27], v[26:27], s[74:75] op_sel_hi:[1,0]
	v_mfma_f32_16x16x32_bf16 v[58:61], v[86:89], v[82:85], v[58:61]
	v_mul_f32_e64 v24, v24, s74
	v_mul_f32_e64 v25, v25, s74
	v_pk_mul_f32 v[56:57], v[56:57], s[74:75] op_sel_hi:[1,0]
	v_pk_mul_f32 v[54:55], v[54:55], s[74:75] op_sel_hi:[1,0]
	v_mfma_f32_16x16x32_bf16 v[62:65], v[90:93], v[82:85], v[62:65]
	v_mfma_f32_16x16x32_bf16 v[28:31], v[94:97], v[82:85], v[30:33]
	ds_read_b128 v[82:85], v14 offset:36864
	s_nop 0
	v_pk_mul_f32 v[60:61], v[60:61], s[74:75] op_sel_hi:[1,0]
	v_pk_mul_f32 v[58:59], v[58:59], s[74:75] op_sel_hi:[1,0]
	s_waitcnt lgkmcnt(0)
	v_mfma_f32_16x16x32_bf16 v[74:77], v[70:73], v[82:85], v[74:77]
	v_lshlrev_b64 v[32:33], 12, v[98:99]
	v_lshlrev_b64 v[98:99], 12, v[100:101]
	v_lshlrev_b64 v[100:101], 12, v[102:103]
	v_mfma_f32_16x16x32_bf16 v[78:81], v[86:89], v[82:85], v[78:81]
	v_lshl_add_u64 v[102:103], v[6:7], 0, s[78:79]
	v_lshl_add_u64 v[32:33], v[102:103], 0, v[32:33]
	v_pk_mul_f32 v[64:65], v[64:65], s[74:75] op_sel_hi:[1,0]
	v_mfma_f32_16x16x32_bf16 v[6:9], v[90:93], v[82:85], v[8:11]
	v_mul_f32_e64 v62, v62, s74
	v_mul_f32_e64 v63, v63, s74
	v_pk_mul_f32 v[30:31], v[30:31], s[74:75] op_sel_hi:[1,0]
	v_pk_mul_f32 v[28:29], v[28:29], s[74:75] op_sel_hi:[1,0]
	v_mfma_f32_16x16x32_bf16 v[66:69], v[94:97], v[82:85], v[66:69]
	ds_read_b128 v[82:85], v14 offset:38912
	v_lshl_add_u64 v[10:11], v[102:103], 0, v[106:107]
	v_lshl_add_u64 v[10:11], v[10:11], 0, v[4:5]
	s_waitcnt lgkmcnt(0)
	v_mfma_f32_16x16x32_bf16 v[14:17], v[70:73], v[82:85], v[16:19]
	v_lshl_add_u64 v[70:71], v[102:103], 0, v[98:99]
	v_lshl_add_u64 v[72:73], v[102:103], 0, v[100:101]
	v_mfma_f32_16x16x32_bf16 v[18:21], v[86:89], v[82:85], v[20:23]
	v_lshl_add_u64 v[86:87], v[72:73], 0, v[4:5]
	s_barrier
	v_mfma_f32_16x16x32_bf16 v[38:41], v[90:93], v[82:85], v[38:41]
	v_lshl_add_u64 v[22:23], v[32:33], 0, v[4:5]
	v_lshl_add_u64 v[32:33], v[70:71], 0, v[4:5]
	v_pk_mul_f32 v[72:73], v[76:77], s[74:75] op_sel_hi:[1,0]
	v_mfma_f32_16x16x32_bf16 v[46:49], v[94:97], v[82:85], v[46:49]
	v_mul_f32_e64 v70, v74, s74
	v_mul_f32_e64 v71, v75, s74
	v_pk_mul_f32 v[76:77], v[80:81], s[74:75] op_sel_hi:[1,0]
	v_pk_mul_f32 v[74:75], v[78:79], s[74:75] op_sel_hi:[1,0]
	v_pk_mul_f32 v[8:9], v[8:9], s[74:75] op_sel_hi:[1,0]
	v_pk_mul_f32 v[6:7], v[6:7], s[74:75] op_sel_hi:[1,0]
	v_pk_mul_f32 v[68:69], v[68:69], s[74:75] op_sel_hi:[1,0]
	v_pk_mul_f32 v[66:67], v[66:67], s[74:75] op_sel_hi:[1,0]
	v_pk_mul_f32 v[16:17], v[16:17], s[74:75] op_sel_hi:[1,0]
	v_pk_mul_f32 v[14:15], v[14:15], s[74:75] op_sel_hi:[1,0]
	v_pk_mul_f32 v[20:21], v[20:21], s[74:75] op_sel_hi:[1,0]
	v_pk_mul_f32 v[18:19], v[18:19], s[74:75] op_sel_hi:[1,0]
	v_pk_mul_f32 v[40:41], v[40:41], s[74:75] op_sel_hi:[1,0]
	v_pk_mul_f32 v[38:39], v[38:39], s[74:75] op_sel_hi:[1,0]
	v_pk_mul_f32 v[48:49], v[48:49], s[74:75] op_sel_hi:[1,0]
	v_pk_mul_f32 v[46:47], v[46:47], s[74:75] op_sel_hi:[1,0]
	global_store_dwordx4 v[10:11], v[34:37], off
	global_store_dwordx4 v[10:11], v[42:45], off offset:64
	global_store_dwordx4 v[10:11], v[50:53], off offset:128
	global_store_dwordx4 v[10:11], v[24:27], off offset:192
	global_store_dwordx4 v[22:23], v[54:57], off
	global_store_dwordx4 v[22:23], v[58:61], off offset:64
	global_store_dwordx4 v[22:23], v[62:65], off offset:128
	global_store_dwordx4 v[22:23], v[28:31], off offset:192
	global_store_dwordx4 v[32:33], v[70:73], off
	global_store_dwordx4 v[32:33], v[74:77], off offset:64
	global_store_dwordx4 v[32:33], v[6:9], off offset:128
	global_store_dwordx4 v[32:33], v[66:69], off offset:192
	global_store_dwordx4 v[86:87], v[14:17], off
	global_store_dwordx4 v[86:87], v[18:21], off offset:64
	global_store_dwordx4 v[86:87], v[38:41], off offset:128
	global_store_dwordx4 v[86:87], v[46:49], off offset:192
	s_cbranch_scc1 .LBB0_1295
	v_readlane_b32 s94, v252, 0
	v_readlane_b32 s95, v252, 1
	s_cmpk_lg_i32 s33, 0x100
	s_cbranch_scc1 .LBB0_1297
; DEV void store_bf4(bf16_t* p, f32x4 v) { uint2 w; w.x = cvt_pk_bf16(v[0], v[1]); w.y = cvt_pk_bf16(v[2], v[3]); *(uint2*)p = w; }
; DEV float wave_max(float v) {
; #pragma unroll
;     for (int o = 32; o >= 1; o >>= 1) v = fmaxf(v, __shfl_xor(v, o));
;     return v;
; }
; __global__ void __launch_bounds__(512) hymba_fwd(Params p) {
;     ...
;     for (int r = bid * 8 + wid; r < TP * 4; r += G * 8) {
;         const f32x4 v = __builtin_nontemporal_load((const f32x4*)(sc + (size_t)r * 256 + lane * 4));
;         const float mx = wave_max(fmaxf(fmaxf(v[0], v[1]), fmaxf(v[2], v[3])));
;         f32x4 e; e[0] = __expf(v[0] - mx); e[1] = __expf(v[1] - mx); e[2] = __expf(v[2] - mx); e[3] = __expf(v[3] - mx);
;         const float inv = 1.f / wave_sum(e[0] + e[1] + e[2] + e[3]);
;         store_bf4(pb + (size_t)(r >> 2) * LDP + (r & 3) * 256 + lane * 4, e * inv);
;     }
	s_waitcnt vmcnt(0)
	s_barrier
	v_mbcnt_lo_u32_b32 v2, -1, 0
	v_mbcnt_hi_u32_b32 v2, -1, v2
	v_lshrrev_b32_e32 v6, 6, v0
	s_lshr_b32 s4, s2, 6
	s_lshl_b32 s4, s4, 11
	s_and_b32 s5, s2, 15
	s_lshl_b32 s5, s5, 7
	s_add_i32 s4, s4, s5
	s_bfe_u32 s5, s2, 0x20004
	v_xor_b32_e32 v8, 32, v2
	v_xor_b32_e32 v9, 16, v2
	v_xor_b32_e32 v10, 8, v2
	v_xor_b32_e32 v11, 4, v2
	v_xor_b32_e32 v12, 2, v2
	v_xor_b32_e32 v13, 1, v2
	v_lshlrev_b32_e32 v8, 2, v8
	v_lshlrev_b32_e32 v9, 2, v9
	v_lshlrev_b32_e32 v10, 2, v10
	v_lshlrev_b32_e32 v11, 2, v11
	v_lshlrev_b32_e32 v12, 2, v12
	v_lshlrev_b32_e32 v13, 2, v13
	v_add_u32_e32 v1, s4, v6
	s_lshl_b32 s6, s5, 10
	v_lshlrev_b32_e32 v14, 12, v1
	v_lshl_add_u32 v15, v2, 4, s6
	v_add_u32_e32 v14, v14, v15
	v_mov_b32_e32 v15, 0
	s_mov_b64 s[6:7], 0x1ef39000
	v_lshl_add_u64 v[4:5], v[158:159], 0, s[6:7]
	v_lshl_add_u64 v[4:5], v[4:5], 0, v[14:15]
	s_mov_b64 s[6:7], 0x20f39000
	v_lshl_add_u64 v[20:21], v[158:159], 0, s[6:7]
	s_movk_i32 s12, 0x880
	v_mad_i64_i32 v[20:21], s[16:17], v1, s12, v[20:21]
	s_lshl_b32 s6, s5, 9
	v_lshl_add_u32 v14, v2, 3, s6
	v_lshl_add_u64 v[20:21], v[20:21], 0, v[14:15]
	s_mov_b64 s[8:9], 0x8000
	s_mov_b64 s[10:11], 0x4400
	s_mov_b64 s[18:19], 0xffffffff
	s_mov_b32 s20, 0xffff
	s_mov_b32 s21, 0xffff
	global_load_dwordx4 v[24:27], v[4:5], off nt
	v_lshl_add_u64 v[4:5], v[4:5], 0, s[8:9]
	global_load_dwordx4 v[28:31], v[4:5], off nt
	v_lshl_add_u64 v[4:5], v[4:5], 0, s[8:9]
	global_load_dwordx4 v[32:35], v[4:5], off nt
	v_lshl_add_u64 v[4:5], v[4:5], 0, s[8:9]
	global_load_dwordx4 v[36:39], v[4:5], off nt
	v_lshl_add_u64 v[4:5], v[4:5], 0, s[8:9]
	global_load_dwordx4 v[40:43], v[4:5], off nt
	v_lshl_add_u64 v[4:5], v[4:5], 0, s[8:9]
	global_load_dwordx4 v[44:47], v[4:5], off nt
	v_lshl_add_u64 v[4:5], v[4:5], 0, s[8:9]
	global_load_dwordx4 v[48:51], v[4:5], off nt
	v_lshl_add_u64 v[4:5], v[4:5], 0, s[8:9]
	global_load_dwordx4 v[52:55], v[4:5], off nt
	v_lshl_add_u64 v[4:5], v[4:5], 0, s[8:9]
	s_waitcnt vmcnt(4)
	v_max_f32_e32 v56, v27, v27
	v_max_f32_e32 v60, v26, v26
	v_max_f32_e32 v56, v60, v56
	v_max3_f32 v56, v24, v25, v56
	v_max_f32_e32 v57, v31, v31
	v_max_f32_e32 v61, v30, v30
	v_max_f32_e32 v57, v61, v57
	v_max3_f32 v57, v28, v29, v57
	v_max_f32_e32 v58, v35, v35
	v_max_f32_e32 v62, v34, v34
	v_max_f32_e32 v58, v62, v58
	v_max3_f32 v58, v32, v33, v58
	v_max_f32_e32 v59, v39, v39
	v_max_f32_e32 v63, v38, v38
	v_max_f32_e32 v59, v63, v59
	v_max3_f32 v59, v36, v37, v59
	v_mov_b32_e32 v69, v56
	v_mov_b32_e32 v70, v56
	s_nop 1
	v_permlane32_swap_b32_e32 v69, v70
	v_cndmask_b32_e64 v60, v69, v70, s[18:19]
	v_mov_b32_e32 v69, v57
	v_mov_b32_e32 v70, v57
	s_nop 1
	v_permlane32_swap_b32_e32 v69, v70
	v_cndmask_b32_e64 v61, v69, v70, s[18:19]
	v_mov_b32_e32 v69, v58
	v_mov_b32_e32 v70, v58
	s_nop 1
	v_permlane32_swap_b32_e32 v69, v70
	v_cndmask_b32_e64 v62, v69, v70, s[18:19]
	v_mov_b32_e32 v69, v59
	v_mov_b32_e32 v70, v59
	s_nop 1
	v_permlane32_swap_b32_e32 v69, v70
	v_cndmask_b32_e64 v63, v69, v70, s[18:19]
	v_max_f32_e32 v60, v60, v60
	v_max_f32_e32 v56, v56, v60
	v_max_f32_e32 v61, v61, v61
	v_max_f32_e32 v57, v57, v61
	v_max_f32_e32 v62, v62, v62
	v_max_f32_e32 v58, v58, v62
	v_max_f32_e32 v63, v63, v63
	v_max_f32_e32 v59, v59, v63
	v_mov_b32_e32 v69, v56
	v_mov_b32_e32 v70, v56
	s_nop 1
	v_permlane16_swap_b32_e32 v69, v70
	v_cndmask_b32_e64 v60, v69, v70, s[20:21]
	v_mov_b32_e32 v69, v57
	v_mov_b32_e32 v70, v57
	s_nop 1
	v_permlane16_swap_b32_e32 v69, v70
	v_cndmask_b32_e64 v61, v69, v70, s[20:21]
	v_mov_b32_e32 v69, v58
	v_mov_b32_e32 v70, v58
	s_nop 1
	v_permlane16_swap_b32_e32 v69, v70
	v_cndmask_b32_e64 v62, v69, v70, s[20:21]
	v_mov_b32_e32 v69, v59
	v_mov_b32_e32 v70, v59
	s_nop 1
	v_permlane16_swap_b32_e32 v69, v70
	v_cndmask_b32_e64 v63, v69, v70, s[20:21]
	v_max_f32_e32 v60, v60, v60
	v_max_f32_e32 v56, v56, v60
	v_max_f32_e32 v61, v61, v61
	v_max_f32_e32 v57, v57, v61
	v_max_f32_e32 v62, v62, v62
	v_max_f32_e32 v58, v58, v62
	v_max_f32_e32 v63, v63, v63
	v_max_f32_e32 v59, v59, v63
	v_mov_b32_dpp v60, v56 row_ror:8 row_mask:0xf bank_mask:0xf
	v_mov_b32_dpp v61, v57 row_ror:8 row_mask:0xf bank_mask:0xf
	v_mov_b32_dpp v62, v58 row_ror:8 row_mask:0xf bank_mask:0xf
	v_mov_b32_dpp v63, v59 row_ror:8 row_mask:0xf bank_mask:0xf
	v_max_f32_e32 v60, v60, v60
	v_max_f32_e32 v56, v56, v60
	v_max_f32_e32 v61, v61, v61
	v_max_f32_e32 v57, v57, v61
	v_max_f32_e32 v62, v62, v62
	v_max_f32_e32 v58, v58, v62
	v_max_f32_e32 v63, v63, v63
	v_max_f32_e32 v59, v59, v63
	v_mov_b32_dpp v69, v56 row_shr:4 row_mask:0xf bank_mask:0xa
	v_mov_b32_dpp v69, v56 row_shl:4 row_mask:0xf bank_mask:0x5
	v_mov_b32_e32 v60, v69
	v_mov_b32_dpp v69, v57 row_shr:4 row_mask:0xf bank_mask:0xa
	v_mov_b32_dpp v69, v57 row_shl:4 row_mask:0xf bank_mask:0x5
	v_mov_b32_e32 v61, v69
	v_mov_b32_dpp v69, v58 row_shr:4 row_mask:0xf bank_mask:0xa
	v_mov_b32_dpp v69, v58 row_shl:4 row_mask:0xf bank_mask:0x5
	v_mov_b32_e32 v62, v69
	v_mov_b32_dpp v69, v59 row_shr:4 row_mask:0xf bank_mask:0xa
	v_mov_b32_dpp v69, v59 row_shl:4 row_mask:0xf bank_mask:0x5
	v_mov_b32_e32 v63, v69
	v_max_f32_e32 v60, v60, v60
	v_max_f32_e32 v56, v56, v60
	v_max_f32_e32 v61, v61, v61
	v_max_f32_e32 v57, v57, v61
	v_max_f32_e32 v62, v62, v62
	v_max_f32_e32 v58, v58, v62
	v_max_f32_e32 v63, v63, v63
	v_max_f32_e32 v59, v59, v63
	v_mov_b32_dpp v60, v56 quad_perm:[2,3,0,1] row_mask:0xf bank_mask:0xf
	v_mov_b32_dpp v61, v57 quad_perm:[2,3,0,1] row_mask:0xf bank_mask:0xf
	v_mov_b32_dpp v62, v58 quad_perm:[2,3,0,1] row_mask:0xf bank_mask:0xf
	v_mov_b32_dpp v63, v59 quad_perm:[2,3,0,1] row_mask:0xf bank_mask:0xf
	v_max_f32_e32 v60, v60, v60
	v_max_f32_e32 v56, v56, v60
; DEV float wave_sum(float v) {
; #pragma unroll
;     for (int o = 32; o >= 1; o >>= 1) v += __shfl_xor(v, o);
;     return v;
; }
; __global__ void __launch_bounds__(512) hymba_fwd(Params p) {
;     ...
;         const float mx = wave_max(fmaxf(fmaxf(v[0], v[1]), fmaxf(v[2], v[3])));
;         f32x4 e; e[0] = __expf(v[0] - mx); e[1] = __expf(v[1] - mx); e[2] = __expf(v[2] - mx); e[3] = __expf(v[3] - mx);
;         const float inv = 1.f / wave_sum(e[0] + e[1] + e[2] + e[3]);
	v_max_f32_e32 v61, v61, v61
	v_max_f32_e32 v57, v57, v61
	v_max_f32_e32 v62, v62, v62
	v_max_f32_e32 v58, v58, v62
	v_max_f32_e32 v63, v63, v63
	v_max_f32_e32 v59, v59, v63
	v_mov_b32_dpp v60, v56 quad_perm:[1,0,3,2] row_mask:0xf bank_mask:0xf
	v_mov_b32_dpp v61, v57 quad_perm:[1,0,3,2] row_mask:0xf bank_mask:0xf
	v_mov_b32_dpp v62, v58 quad_perm:[1,0,3,2] row_mask:0xf bank_mask:0xf
	v_mov_b32_dpp v63, v59 quad_perm:[1,0,3,2] row_mask:0xf bank_mask:0xf
	v_max_f32_e32 v60, v60, v60
	v_max_f32_e32 v56, v56, v60
	v_max_f32_e32 v61, v61, v61
	v_max_f32_e32 v57, v57, v61
	v_max_f32_e32 v62, v62, v62
	v_max_f32_e32 v58, v58, v62
	v_max_f32_e32 v63, v63, v63
	v_max_f32_e32 v59, v59, v63
	v_sub_f32_e32 v24, v24, v56
	v_sub_f32_e32 v25, v25, v56
	v_sub_f32_e32 v26, v26, v56
	v_sub_f32_e32 v27, v27, v56
	v_mul_f32_e32 v24, 0x3fb8aa3b, v24
	v_mul_f32_e32 v25, 0x3fb8aa3b, v25
	v_mul_f32_e32 v26, 0x3fb8aa3b, v26
	v_mul_f32_e32 v27, 0x3fb8aa3b, v27
	v_sub_f32_e32 v28, v28, v57
	v_sub_f32_e32 v29, v29, v57
	v_sub_f32_e32 v30, v30, v57
	v_sub_f32_e32 v31, v31, v57
	v_mul_f32_e32 v28, 0x3fb8aa3b, v28
	v_mul_f32_e32 v29, 0x3fb8aa3b, v29
	v_mul_f32_e32 v30, 0x3fb8aa3b, v30
	v_mul_f32_e32 v31, 0x3fb8aa3b, v31
	v_sub_f32_e32 v32, v32, v58
	v_sub_f32_e32 v33, v33, v58
	v_sub_f32_e32 v34, v34, v58
	v_sub_f32_e32 v35, v35, v58
	v_mul_f32_e32 v32, 0x3fb8aa3b, v32
	v_mul_f32_e32 v33, 0x3fb8aa3b, v33
	v_mul_f32_e32 v34, 0x3fb8aa3b, v34
	v_mul_f32_e32 v35, 0x3fb8aa3b, v35
	v_sub_f32_e32 v36, v36, v59
	v_sub_f32_e32 v37, v37, v59
	v_sub_f32_e32 v38, v38, v59
	v_sub_f32_e32 v39, v39, v59
	v_mul_f32_e32 v36, 0x3fb8aa3b, v36
	v_mul_f32_e32 v37, 0x3fb8aa3b, v37
	v_mul_f32_e32 v38, 0x3fb8aa3b, v38
	v_mul_f32_e32 v39, 0x3fb8aa3b, v39
	v_exp_f32_e32 v24, v24
	v_exp_f32_e32 v25, v25
	v_exp_f32_e32 v26, v26
	v_exp_f32_e32 v27, v27
	v_exp_f32_e32 v28, v28
	v_exp_f32_e32 v29, v29
	v_exp_f32_e32 v30, v30
	v_exp_f32_e32 v31, v31
	v_exp_f32_e32 v32, v32
	v_exp_f32_e32 v33, v33
	v_exp_f32_e32 v34, v34
	v_exp_f32_e32 v35, v35
	v_exp_f32_e32 v36, v36
	v_exp_f32_e32 v37, v37
	v_exp_f32_e32 v38, v38
	v_exp_f32_e32 v39, v39
	v_add_f32_e32 v56, v24, v25
	v_add_f32_e32 v56, v26, v56
	v_add_f32_e32 v56, v27, v56
	v_add_f32_e32 v57, v28, v29
	v_add_f32_e32 v57, v30, v57
	v_add_f32_e32 v57, v31, v57
	v_add_f32_e32 v58, v32, v33
	v_add_f32_e32 v58, v34, v58
	v_add_f32_e32 v58, v35, v58
	v_add_f32_e32 v59, v36, v37
	v_add_f32_e32 v59, v38, v59
	v_add_f32_e32 v59, v39, v59
	v_mov_b32_e32 v69, v56
	v_mov_b32_e32 v70, v56
	s_nop 1
	v_permlane32_swap_b32_e32 v69, v70
	v_cndmask_b32_e64 v60, v69, v70, s[18:19]
	v_mov_b32_e32 v69, v57
	v_mov_b32_e32 v70, v57
	s_nop 1
	v_permlane32_swap_b32_e32 v69, v70
	v_cndmask_b32_e64 v61, v69, v70, s[18:19]
	v_mov_b32_e32 v69, v58
	v_mov_b32_e32 v70, v58
	s_nop 1
	v_permlane32_swap_b32_e32 v69, v70
	v_cndmask_b32_e64 v62, v69, v70, s[18:19]
	v_mov_b32_e32 v69, v59
	v_mov_b32_e32 v70, v59
	s_nop 1
	v_permlane32_swap_b32_e32 v69, v70
	v_cndmask_b32_e64 v63, v69, v70, s[18:19]
	v_add_f32_e32 v56, v56, v60
	v_add_f32_e32 v57, v57, v61
	v_add_f32_e32 v58, v58, v62
	v_add_f32_e32 v59, v59, v63
	v_mov_b32_e32 v69, v56
	v_mov_b32_e32 v70, v56
	s_nop 1
	v_permlane16_swap_b32_e32 v69, v70
	v_cndmask_b32_e64 v60, v69, v70, s[20:21]
	v_mov_b32_e32 v69, v57
	v_mov_b32_e32 v70, v57
	s_nop 1
	v_permlane16_swap_b32_e32 v69, v70
	v_cndmask_b32_e64 v61, v69, v70, s[20:21]
	v_mov_b32_e32 v69, v58
	v_mov_b32_e32 v70, v58
	s_nop 1
	v_permlane16_swap_b32_e32 v69, v70
	v_cndmask_b32_e64 v62, v69, v70, s[20:21]
	v_mov_b32_e32 v69, v59
	v_mov_b32_e32 v70, v59
	s_nop 1
	v_permlane16_swap_b32_e32 v69, v70
	v_cndmask_b32_e64 v63, v69, v70, s[20:21]
	v_add_f32_e32 v56, v56, v60
	v_add_f32_e32 v57, v57, v61
	v_add_f32_e32 v58, v58, v62
	v_add_f32_e32 v59, v59, v63
	v_mov_b32_dpp v60, v56 row_ror:8 row_mask:0xf bank_mask:0xf
	v_mov_b32_dpp v61, v57 row_ror:8 row_mask:0xf bank_mask:0xf
	v_mov_b32_dpp v62, v58 row_ror:8 row_mask:0xf bank_mask:0xf
	v_mov_b32_dpp v63, v59 row_ror:8 row_mask:0xf bank_mask:0xf
	v_add_f32_e32 v56, v56, v60
	v_add_f32_e32 v57, v57, v61
	v_add_f32_e32 v58, v58, v62
	v_add_f32_e32 v59, v59, v63
	v_mov_b32_dpp v69, v56 row_shr:4 row_mask:0xf bank_mask:0xa
	v_mov_b32_dpp v69, v56 row_shl:4 row_mask:0xf bank_mask:0x5
	v_mov_b32_e32 v60, v69
	v_mov_b32_dpp v69, v57 row_shr:4 row_mask:0xf bank_mask:0xa
	v_mov_b32_dpp v69, v57 row_shl:4 row_mask:0xf bank_mask:0x5
	v_mov_b32_e32 v61, v69
	v_mov_b32_dpp v69, v58 row_shr:4 row_mask:0xf bank_mask:0xa
	v_mov_b32_dpp v69, v58 row_shl:4 row_mask:0xf bank_mask:0x5
	v_mov_b32_e32 v62, v69
	v_mov_b32_dpp v69, v59 row_shr:4 row_mask:0xf bank_mask:0xa
	v_mov_b32_dpp v69, v59 row_shl:4 row_mask:0xf bank_mask:0x5
	v_mov_b32_e32 v63, v69
	v_add_f32_e32 v56, v56, v60
	v_add_f32_e32 v57, v57, v61
	v_add_f32_e32 v58, v58, v62
	v_add_f32_e32 v59, v59, v63
	v_mov_b32_dpp v60, v56 quad_perm:[2,3,0,1] row_mask:0xf bank_mask:0xf
	v_mov_b32_dpp v61, v57 quad_perm:[2,3,0,1] row_mask:0xf bank_mask:0xf
	v_mov_b32_dpp v62, v58 quad_perm:[2,3,0,1] row_mask:0xf bank_mask:0xf
	v_mov_b32_dpp v63, v59 quad_perm:[2,3,0,1] row_mask:0xf bank_mask:0xf
	v_add_f32_e32 v56, v56, v60
	v_add_f32_e32 v57, v57, v61
	v_add_f32_e32 v58, v58, v62
	v_add_f32_e32 v59, v59, v63
	v_mov_b32_dpp v60, v56 quad_perm:[1,0,3,2] row_mask:0xf bank_mask:0xf
	v_mov_b32_dpp v61, v57 quad_perm:[1,0,3,2] row_mask:0xf bank_mask:0xf
	v_mov_b32_dpp v62, v58 quad_perm:[1,0,3,2] row_mask:0xf bank_mask:0xf
	v_mov_b32_dpp v63, v59 quad_perm:[1,0,3,2] row_mask:0xf bank_mask:0xf
	v_add_f32_e32 v56, v56, v60
	v_add_f32_e32 v57, v57, v61
	v_add_f32_e32 v58, v58, v62
	v_add_f32_e32 v59, v59, v63
; DEV void store_bf4(bf16_t* p, f32x4 v) { uint2 w; w.x = cvt_pk_bf16(v[0], v[1]); w.y = cvt_pk_bf16(v[2], v[3]); *(uint2*)p = w; }
; DEV float wave_max(float v) {
; #pragma unroll
;     for (int o = 32; o >= 1; o >>= 1) v = fmaxf(v, __shfl_xor(v, o));
;     return v;
; }
; __global__ void __launch_bounds__(512) hymba_fwd(Params p) {
;     ...
;         const f32x4 v = __builtin_nontemporal_load((const f32x4*)(sc + (size_t)r * 256 + lane * 4));
;         const float mx = wave_max(fmaxf(fmaxf(v[0], v[1]), fmaxf(v[2], v[3])));
;         f32x4 e; e[0] = __expf(v[0] - mx); e[1] = __expf(v[1] - mx); e[2] = __expf(v[2] - mx); e[3] = __expf(v[3] - mx);
;         const float inv = 1.f / wave_sum(e[0] + e[1] + e[2] + e[3]);
;         store_bf4(pb + (size_t)(r >> 2) * LDP + (r & 3) * 256 + lane * 4, e * inv);
	v_div_scale_f32 v64, s[16:17], v56, v56, 1.0
	v_rcp_f32_e32 v65, v64
	v_div_scale_f32 v66, vcc, 1.0, v56, 1.0
	v_fma_f32 v67, -v64, v65, 1.0
	v_fmac_f32_e32 v65, v67, v65
	v_mul_f32_e32 v67, v66, v65
	v_fma_f32 v68, -v64, v67, v66
	v_fmac_f32_e32 v67, v68, v65
	v_fma_f32 v64, -v64, v67, v66
	v_div_fmas_f32 v64, v64, v65, v67
	v_div_fixup_f32 v56, v64, v56, 1.0
	v_mul_f32_e32 v24, v24, v56
	v_mul_f32_e32 v25, v25, v56
	v_mul_f32_e32 v26, v26, v56
	v_mul_f32_e32 v27, v27, v56
	v_cvt_pk_bf16_f32 v24, v24, v25
	v_cvt_pk_bf16_f32 v25, v26, v27
	global_store_dwordx2 v[20:21], v[24:25], off
	v_lshl_add_u64 v[20:21], v[20:21], 0, s[10:11]
	v_div_scale_f32 v64, s[16:17], v57, v57, 1.0
	v_rcp_f32_e32 v65, v64
	v_div_scale_f32 v66, vcc, 1.0, v57, 1.0
	v_fma_f32 v67, -v64, v65, 1.0
	v_fmac_f32_e32 v65, v67, v65
	v_mul_f32_e32 v67, v66, v65
	v_fma_f32 v68, -v64, v67, v66
	v_fmac_f32_e32 v67, v68, v65
	v_fma_f32 v64, -v64, v67, v66
	v_div_fmas_f32 v64, v64, v65, v67
	v_div_fixup_f32 v57, v64, v57, 1.0
	v_mul_f32_e32 v28, v28, v57
	v_mul_f32_e32 v29, v29, v57
	v_mul_f32_e32 v30, v30, v57
	v_mul_f32_e32 v31, v31, v57
	v_cvt_pk_bf16_f32 v28, v28, v29
	v_cvt_pk_bf16_f32 v29, v30, v31
	global_store_dwordx2 v[20:21], v[28:29], off
	v_lshl_add_u64 v[20:21], v[20:21], 0, s[10:11]
	v_div_scale_f32 v64, s[16:17], v58, v58, 1.0
	v_rcp_f32_e32 v65, v64
	v_div_scale_f32 v66, vcc, 1.0, v58, 1.0
	v_fma_f32 v67, -v64, v65, 1.0
	v_fmac_f32_e32 v65, v67, v65
	v_mul_f32_e32 v67, v66, v65
	v_fma_f32 v68, -v64, v67, v66
	v_fmac_f32_e32 v67, v68, v65
	v_fma_f32 v64, -v64, v67, v66
	v_div_fmas_f32 v64, v64, v65, v67
	v_div_fixup_f32 v58, v64, v58, 1.0
	v_mul_f32_e32 v32, v32, v58
	v_mul_f32_e32 v33, v33, v58
	v_mul_f32_e32 v34, v34, v58
	v_mul_f32_e32 v35, v35, v58
	v_cvt_pk_bf16_f32 v32, v32, v33
	v_cvt_pk_bf16_f32 v33, v34, v35
	global_store_dwordx2 v[20:21], v[32:33], off
	v_lshl_add_u64 v[20:21], v[20:21], 0, s[10:11]
	v_div_scale_f32 v64, s[16:17], v59, v59, 1.0
	v_rcp_f32_e32 v65, v64
	v_div_scale_f32 v66, vcc, 1.0, v59, 1.0
	v_fma_f32 v67, -v64, v65, 1.0
	v_fmac_f32_e32 v65, v67, v65
	v_mul_f32_e32 v67, v66, v65
	v_fma_f32 v68, -v64, v67, v66
	v_fmac_f32_e32 v67, v68, v65
	v_fma_f32 v64, -v64, v67, v66
	v_div_fmas_f32 v64, v64, v65, v67
	v_div_fixup_f32 v59, v64, v59, 1.0
	v_mul_f32_e32 v36, v36, v59
	v_mul_f32_e32 v37, v37, v59
	v_mul_f32_e32 v38, v38, v59
	v_mul_f32_e32 v39, v39, v59
	v_cvt_pk_bf16_f32 v36, v36, v37
	v_cvt_pk_bf16_f32 v37, v38, v39
	global_store_dwordx2 v[20:21], v[36:37], off
	v_lshl_add_u64 v[20:21], v[20:21], 0, s[10:11]
	global_load_dwordx4 v[24:27], v[4:5], off nt
	v_lshl_add_u64 v[4:5], v[4:5], 0, s[8:9]
	global_load_dwordx4 v[28:31], v[4:5], off nt
	v_lshl_add_u64 v[4:5], v[4:5], 0, s[8:9]
	global_load_dwordx4 v[32:35], v[4:5], off nt
	v_lshl_add_u64 v[4:5], v[4:5], 0, s[8:9]
	global_load_dwordx4 v[36:39], v[4:5], off nt
	v_lshl_add_u64 v[4:5], v[4:5], 0, s[8:9]
	s_waitcnt vmcnt(8)
	v_max_f32_e32 v56, v43, v43
	v_max_f32_e32 v60, v42, v42
	v_max_f32_e32 v56, v60, v56
	v_max3_f32 v56, v40, v41, v56
	v_max_f32_e32 v57, v47, v47
	v_max_f32_e32 v61, v46, v46
	v_max_f32_e32 v57, v61, v57
	v_max3_f32 v57, v44, v45, v57
	v_max_f32_e32 v58, v51, v51
	v_max_f32_e32 v62, v50, v50
	v_max_f32_e32 v58, v62, v58
	v_max3_f32 v58, v48, v49, v58
	v_max_f32_e32 v59, v55, v55
	v_max_f32_e32 v63, v54, v54
	v_max_f32_e32 v59, v63, v59
	v_max3_f32 v59, v52, v53, v59
	v_mov_b32_e32 v69, v56
	v_mov_b32_e32 v70, v56
	s_nop 1
	v_permlane32_swap_b32_e32 v69, v70
	v_cndmask_b32_e64 v60, v69, v70, s[18:19]
	v_mov_b32_e32 v69, v57
	v_mov_b32_e32 v70, v57
	s_nop 1
	v_permlane32_swap_b32_e32 v69, v70
	v_cndmask_b32_e64 v61, v69, v70, s[18:19]
	v_mov_b32_e32 v69, v58
	v_mov_b32_e32 v70, v58
	s_nop 1
	v_permlane32_swap_b32_e32 v69, v70
	v_cndmask_b32_e64 v62, v69, v70, s[18:19]
	v_mov_b32_e32 v69, v59
	v_mov_b32_e32 v70, v59
	s_nop 1
	v_permlane32_swap_b32_e32 v69, v70
	v_cndmask_b32_e64 v63, v69, v70, s[18:19]
	v_max_f32_e32 v60, v60, v60
	v_max_f32_e32 v56, v56, v60
	v_max_f32_e32 v61, v61, v61
	v_max_f32_e32 v57, v57, v61
	v_max_f32_e32 v62, v62, v62
	v_max_f32_e32 v58, v58, v62
	v_max_f32_e32 v63, v63, v63
	v_max_f32_e32 v59, v59, v63
	v_mov_b32_e32 v69, v56
	v_mov_b32_e32 v70, v56
	s_nop 1
	v_permlane16_swap_b32_e32 v69, v70
	v_cndmask_b32_e64 v60, v69, v70, s[20:21]
	v_mov_b32_e32 v69, v57
	v_mov_b32_e32 v70, v57
	s_nop 1
	v_permlane16_swap_b32_e32 v69, v70
	v_cndmask_b32_e64 v61, v69, v70, s[20:21]
	v_mov_b32_e32 v69, v58
	v_mov_b32_e32 v70, v58
	s_nop 1
	v_permlane16_swap_b32_e32 v69, v70
	v_cndmask_b32_e64 v62, v69, v70, s[20:21]
	v_mov_b32_e32 v69, v59
	v_mov_b32_e32 v70, v59
	s_nop 1
	v_permlane16_swap_b32_e32 v69, v70
	v_cndmask_b32_e64 v63, v69, v70, s[20:21]
	v_max_f32_e32 v60, v60, v60
	v_max_f32_e32 v56, v56, v60
	v_max_f32_e32 v61, v61, v61
	v_max_f32_e32 v57, v57, v61
	v_max_f32_e32 v62, v62, v62
	v_max_f32_e32 v58, v58, v62
	v_max_f32_e32 v63, v63, v63
	v_max_f32_e32 v59, v59, v63
	v_mov_b32_dpp v60, v56 row_ror:8 row_mask:0xf bank_mask:0xf
	v_mov_b32_dpp v61, v57 row_ror:8 row_mask:0xf bank_mask:0xf
	v_mov_b32_dpp v62, v58 row_ror:8 row_mask:0xf bank_mask:0xf
	v_mov_b32_dpp v63, v59 row_ror:8 row_mask:0xf bank_mask:0xf
	v_max_f32_e32 v60, v60, v60
	v_max_f32_e32 v56, v56, v60
	v_max_f32_e32 v61, v61, v61
	v_max_f32_e32 v57, v57, v61
	v_max_f32_e32 v62, v62, v62
	v_max_f32_e32 v58, v58, v62
	v_max_f32_e32 v63, v63, v63
	v_max_f32_e32 v59, v59, v63
	v_mov_b32_dpp v69, v56 row_shr:4 row_mask:0xf bank_mask:0xa
	v_mov_b32_dpp v69, v56 row_shl:4 row_mask:0xf bank_mask:0x5
	v_mov_b32_e32 v60, v69
	v_mov_b32_dpp v69, v57 row_shr:4 row_mask:0xf bank_mask:0xa
; DEV float wave_sum(float v) {
; #pragma unroll
;     for (int o = 32; o >= 1; o >>= 1) v += __shfl_xor(v, o);
;     return v;
; }
; DEV float wave_max(float v) {
; #pragma unroll
;     for (int o = 32; o >= 1; o >>= 1) v = fmaxf(v, __shfl_xor(v, o));
;     return v;
; }
; __global__ void __launch_bounds__(512) hymba_fwd(Params p) {
;     ...
;         const float mx = wave_max(fmaxf(fmaxf(v[0], v[1]), fmaxf(v[2], v[3])));
;         f32x4 e; e[0] = __expf(v[0] - mx); e[1] = __expf(v[1] - mx); e[2] = __expf(v[2] - mx); e[3] = __expf(v[3] - mx);
;         const float inv = 1.f / wave_sum(e[0] + e[1] + e[2] + e[3]);
	v_mov_b32_dpp v69, v57 row_shl:4 row_mask:0xf bank_mask:0x5
	v_mov_b32_e32 v61, v69
	v_mov_b32_dpp v69, v58 row_shr:4 row_mask:0xf bank_mask:0xa
	v_mov_b32_dpp v69, v58 row_shl:4 row_mask:0xf bank_mask:0x5
	v_mov_b32_e32 v62, v69
	v_mov_b32_dpp v69, v59 row_shr:4 row_mask:0xf bank_mask:0xa
	v_mov_b32_dpp v69, v59 row_shl:4 row_mask:0xf bank_mask:0x5
	v_mov_b32_e32 v63, v69
	v_max_f32_e32 v60, v60, v60
	v_max_f32_e32 v56, v56, v60
	v_max_f32_e32 v61, v61, v61
	v_max_f32_e32 v57, v57, v61
	v_max_f32_e32 v62, v62, v62
	v_max_f32_e32 v58, v58, v62
	v_max_f32_e32 v63, v63, v63
	v_max_f32_e32 v59, v59, v63
	v_mov_b32_dpp v60, v56 quad_perm:[2,3,0,1] row_mask:0xf bank_mask:0xf
	v_mov_b32_dpp v61, v57 quad_perm:[2,3,0,1] row_mask:0xf bank_mask:0xf
	v_mov_b32_dpp v62, v58 quad_perm:[2,3,0,1] row_mask:0xf bank_mask:0xf
	v_mov_b32_dpp v63, v59 quad_perm:[2,3,0,1] row_mask:0xf bank_mask:0xf
	v_max_f32_e32 v60, v60, v60
	v_max_f32_e32 v56, v56, v60
	v_max_f32_e32 v61, v61, v61
	v_max_f32_e32 v57, v57, v61
	v_max_f32_e32 v62, v62, v62
	v_max_f32_e32 v58, v58, v62
	v_max_f32_e32 v63, v63, v63
	v_max_f32_e32 v59, v59, v63
	v_mov_b32_dpp v60, v56 quad_perm:[1,0,3,2] row_mask:0xf bank_mask:0xf
	v_mov_b32_dpp v61, v57 quad_perm:[1,0,3,2] row_mask:0xf bank_mask:0xf
	v_mov_b32_dpp v62, v58 quad_perm:[1,0,3,2] row_mask:0xf bank_mask:0xf
	v_mov_b32_dpp v63, v59 quad_perm:[1,0,3,2] row_mask:0xf bank_mask:0xf
	v_max_f32_e32 v60, v60, v60
	v_max_f32_e32 v56, v56, v60
	v_max_f32_e32 v61, v61, v61
	v_max_f32_e32 v57, v57, v61
	v_max_f32_e32 v62, v62, v62
	v_max_f32_e32 v58, v58, v62
	v_max_f32_e32 v63, v63, v63
	v_max_f32_e32 v59, v59, v63
	v_sub_f32_e32 v40, v40, v56
	v_sub_f32_e32 v41, v41, v56
	v_sub_f32_e32 v42, v42, v56
	v_sub_f32_e32 v43, v43, v56
	v_mul_f32_e32 v40, 0x3fb8aa3b, v40
	v_mul_f32_e32 v41, 0x3fb8aa3b, v41
	v_mul_f32_e32 v42, 0x3fb8aa3b, v42
	v_mul_f32_e32 v43, 0x3fb8aa3b, v43
	v_sub_f32_e32 v44, v44, v57
	v_sub_f32_e32 v45, v45, v57
	v_sub_f32_e32 v46, v46, v57
	v_sub_f32_e32 v47, v47, v57
	v_mul_f32_e32 v44, 0x3fb8aa3b, v44
	v_mul_f32_e32 v45, 0x3fb8aa3b, v45
	v_mul_f32_e32 v46, 0x3fb8aa3b, v46
	v_mul_f32_e32 v47, 0x3fb8aa3b, v47
	v_sub_f32_e32 v48, v48, v58
	v_sub_f32_e32 v49, v49, v58
	v_sub_f32_e32 v50, v50, v58
	v_sub_f32_e32 v51, v51, v58
	v_mul_f32_e32 v48, 0x3fb8aa3b, v48
	v_mul_f32_e32 v49, 0x3fb8aa3b, v49
	v_mul_f32_e32 v50, 0x3fb8aa3b, v50
	v_mul_f32_e32 v51, 0x3fb8aa3b, v51
	v_sub_f32_e32 v52, v52, v59
	v_sub_f32_e32 v53, v53, v59
	v_sub_f32_e32 v54, v54, v59
	v_sub_f32_e32 v55, v55, v59
	v_mul_f32_e32 v52, 0x3fb8aa3b, v52
	v_mul_f32_e32 v53, 0x3fb8aa3b, v53
	v_mul_f32_e32 v54, 0x3fb8aa3b, v54
	v_mul_f32_e32 v55, 0x3fb8aa3b, v55
	v_exp_f32_e32 v40, v40
	v_exp_f32_e32 v41, v41
	v_exp_f32_e32 v42, v42
	v_exp_f32_e32 v43, v43
	v_exp_f32_e32 v44, v44
	v_exp_f32_e32 v45, v45
	v_exp_f32_e32 v46, v46
	v_exp_f32_e32 v47, v47
	v_exp_f32_e32 v48, v48
	v_exp_f32_e32 v49, v49
	v_exp_f32_e32 v50, v50
	v_exp_f32_e32 v51, v51
	v_exp_f32_e32 v52, v52
	v_exp_f32_e32 v53, v53
	v_exp_f32_e32 v54, v54
	v_exp_f32_e32 v55, v55
	v_add_f32_e32 v56, v40, v41
	v_add_f32_e32 v56, v42, v56
	v_add_f32_e32 v56, v43, v56
	v_add_f32_e32 v57, v44, v45
	v_add_f32_e32 v57, v46, v57
	v_add_f32_e32 v57, v47, v57
	v_add_f32_e32 v58, v48, v49
	v_add_f32_e32 v58, v50, v58
	v_add_f32_e32 v58, v51, v58
	v_add_f32_e32 v59, v52, v53
	v_add_f32_e32 v59, v54, v59
	v_add_f32_e32 v59, v55, v59
	v_mov_b32_e32 v69, v56
	v_mov_b32_e32 v70, v56
	s_nop 1
	v_permlane32_swap_b32_e32 v69, v70
	v_cndmask_b32_e64 v60, v69, v70, s[18:19]
	v_mov_b32_e32 v69, v57
	v_mov_b32_e32 v70, v57
	s_nop 1
	v_permlane32_swap_b32_e32 v69, v70
	v_cndmask_b32_e64 v61, v69, v70, s[18:19]
	v_mov_b32_e32 v69, v58
	v_mov_b32_e32 v70, v58
	s_nop 1
	v_permlane32_swap_b32_e32 v69, v70
	v_cndmask_b32_e64 v62, v69, v70, s[18:19]
	v_mov_b32_e32 v69, v59
	v_mov_b32_e32 v70, v59
	s_nop 1
	v_permlane32_swap_b32_e32 v69, v70
	v_cndmask_b32_e64 v63, v69, v70, s[18:19]
	v_add_f32_e32 v56, v56, v60
	v_add_f32_e32 v57, v57, v61
	v_add_f32_e32 v58, v58, v62
	v_add_f32_e32 v59, v59, v63
	v_mov_b32_e32 v69, v56
	v_mov_b32_e32 v70, v56
	s_nop 1
	v_permlane16_swap_b32_e32 v69, v70
	v_cndmask_b32_e64 v60, v69, v70, s[20:21]
	v_mov_b32_e32 v69, v57
	v_mov_b32_e32 v70, v57
	s_nop 1
	v_permlane16_swap_b32_e32 v69, v70
	v_cndmask_b32_e64 v61, v69, v70, s[20:21]
	v_mov_b32_e32 v69, v58
	v_mov_b32_e32 v70, v58
	s_nop 1
	v_permlane16_swap_b32_e32 v69, v70
	v_cndmask_b32_e64 v62, v69, v70, s[20:21]
	v_mov_b32_e32 v69, v59
	v_mov_b32_e32 v70, v59
	s_nop 1
	v_permlane16_swap_b32_e32 v69, v70
	v_cndmask_b32_e64 v63, v69, v70, s[20:21]
	v_add_f32_e32 v56, v56, v60
	v_add_f32_e32 v57, v57, v61
	v_add_f32_e32 v58, v58, v62
	v_add_f32_e32 v59, v59, v63
	v_mov_b32_dpp v60, v56 row_ror:8 row_mask:0xf bank_mask:0xf
	v_mov_b32_dpp v61, v57 row_ror:8 row_mask:0xf bank_mask:0xf
	v_mov_b32_dpp v62, v58 row_ror:8 row_mask:0xf bank_mask:0xf
	v_mov_b32_dpp v63, v59 row_ror:8 row_mask:0xf bank_mask:0xf
	v_add_f32_e32 v56, v56, v60
	v_add_f32_e32 v57, v57, v61
	v_add_f32_e32 v58, v58, v62
	v_add_f32_e32 v59, v59, v63
	v_mov_b32_dpp v69, v56 row_shr:4 row_mask:0xf bank_mask:0xa
	v_mov_b32_dpp v69, v56 row_shl:4 row_mask:0xf bank_mask:0x5
	v_mov_b32_e32 v60, v69
	v_mov_b32_dpp v69, v57 row_shr:4 row_mask:0xf bank_mask:0xa
	v_mov_b32_dpp v69, v57 row_shl:4 row_mask:0xf bank_mask:0x5
	v_mov_b32_e32 v61, v69
	v_mov_b32_dpp v69, v58 row_shr:4 row_mask:0xf bank_mask:0xa
	v_mov_b32_dpp v69, v58 row_shl:4 row_mask:0xf bank_mask:0x5
	v_mov_b32_e32 v62, v69
	v_mov_b32_dpp v69, v59 row_shr:4 row_mask:0xf bank_mask:0xa
	v_mov_b32_dpp v69, v59 row_shl:4 row_mask:0xf bank_mask:0x5
; DEV void store_bf4(bf16_t* p, f32x4 v) { uint2 w; w.x = cvt_pk_bf16(v[0], v[1]); w.y = cvt_pk_bf16(v[2], v[3]); *(uint2*)p = w; }
; DEV float wave_sum(float v) {
; #pragma unroll
;     for (int o = 32; o >= 1; o >>= 1) v += __shfl_xor(v, o);
;     return v;
; }
; DEV float wave_max(float v) {
; #pragma unroll
;     for (int o = 32; o >= 1; o >>= 1) v = fmaxf(v, __shfl_xor(v, o));
;     return v;
; }
; __global__ void __launch_bounds__(512) hymba_fwd(Params p) {
;     ...
;         const f32x4 v = __builtin_nontemporal_load((const f32x4*)(sc + (size_t)r * 256 + lane * 4));
;         const float mx = wave_max(fmaxf(fmaxf(v[0], v[1]), fmaxf(v[2], v[3])));
;         f32x4 e; e[0] = __expf(v[0] - mx); e[1] = __expf(v[1] - mx); e[2] = __expf(v[2] - mx); e[3] = __expf(v[3] - mx);
;         const float inv = 1.f / wave_sum(e[0] + e[1] + e[2] + e[3]);
;         store_bf4(pb + (size_t)(r >> 2) * LDP + (r & 3) * 256 + lane * 4, e * inv);
	v_mov_b32_e32 v63, v69
	v_add_f32_e32 v56, v56, v60
	v_add_f32_e32 v57, v57, v61
	v_add_f32_e32 v58, v58, v62
	v_add_f32_e32 v59, v59, v63
	v_mov_b32_dpp v60, v56 quad_perm:[2,3,0,1] row_mask:0xf bank_mask:0xf
	v_mov_b32_dpp v61, v57 quad_perm:[2,3,0,1] row_mask:0xf bank_mask:0xf
	v_mov_b32_dpp v62, v58 quad_perm:[2,3,0,1] row_mask:0xf bank_mask:0xf
	v_mov_b32_dpp v63, v59 quad_perm:[2,3,0,1] row_mask:0xf bank_mask:0xf
	v_add_f32_e32 v56, v56, v60
	v_add_f32_e32 v57, v57, v61
	v_add_f32_e32 v58, v58, v62
	v_add_f32_e32 v59, v59, v63
	v_mov_b32_dpp v60, v56 quad_perm:[1,0,3,2] row_mask:0xf bank_mask:0xf
	v_mov_b32_dpp v61, v57 quad_perm:[1,0,3,2] row_mask:0xf bank_mask:0xf
	v_mov_b32_dpp v62, v58 quad_perm:[1,0,3,2] row_mask:0xf bank_mask:0xf
	v_mov_b32_dpp v63, v59 quad_perm:[1,0,3,2] row_mask:0xf bank_mask:0xf
	v_add_f32_e32 v56, v56, v60
	v_add_f32_e32 v57, v57, v61
	v_add_f32_e32 v58, v58, v62
	v_add_f32_e32 v59, v59, v63
	v_div_scale_f32 v64, s[16:17], v56, v56, 1.0
	v_rcp_f32_e32 v65, v64
	v_div_scale_f32 v66, vcc, 1.0, v56, 1.0
	v_fma_f32 v67, -v64, v65, 1.0
	v_fmac_f32_e32 v65, v67, v65
	v_mul_f32_e32 v67, v66, v65
	v_fma_f32 v68, -v64, v67, v66
	v_fmac_f32_e32 v67, v68, v65
	v_fma_f32 v64, -v64, v67, v66
	v_div_fmas_f32 v64, v64, v65, v67
	v_div_fixup_f32 v56, v64, v56, 1.0
	v_mul_f32_e32 v40, v40, v56
	v_mul_f32_e32 v41, v41, v56
	v_mul_f32_e32 v42, v42, v56
	v_mul_f32_e32 v43, v43, v56
	v_cvt_pk_bf16_f32 v40, v40, v41
	v_cvt_pk_bf16_f32 v41, v42, v43
	global_store_dwordx2 v[20:21], v[40:41], off
	v_lshl_add_u64 v[20:21], v[20:21], 0, s[10:11]
	v_div_scale_f32 v64, s[16:17], v57, v57, 1.0
	v_rcp_f32_e32 v65, v64
	v_div_scale_f32 v66, vcc, 1.0, v57, 1.0
	v_fma_f32 v67, -v64, v65, 1.0
	v_fmac_f32_e32 v65, v67, v65
	v_mul_f32_e32 v67, v66, v65
	v_fma_f32 v68, -v64, v67, v66
	v_fmac_f32_e32 v67, v68, v65
	v_fma_f32 v64, -v64, v67, v66
	v_div_fmas_f32 v64, v64, v65, v67
	v_div_fixup_f32 v57, v64, v57, 1.0
	v_mul_f32_e32 v44, v44, v57
	v_mul_f32_e32 v45, v45, v57
	v_mul_f32_e32 v46, v46, v57
	v_mul_f32_e32 v47, v47, v57
	v_cvt_pk_bf16_f32 v44, v44, v45
	v_cvt_pk_bf16_f32 v45, v46, v47
	global_store_dwordx2 v[20:21], v[44:45], off
	v_lshl_add_u64 v[20:21], v[20:21], 0, s[10:11]
	v_div_scale_f32 v64, s[16:17], v58, v58, 1.0
	v_rcp_f32_e32 v65, v64
	v_div_scale_f32 v66, vcc, 1.0, v58, 1.0
	v_fma_f32 v67, -v64, v65, 1.0
	v_fmac_f32_e32 v65, v67, v65
	v_mul_f32_e32 v67, v66, v65
	v_fma_f32 v68, -v64, v67, v66
	v_fmac_f32_e32 v67, v68, v65
	v_fma_f32 v64, -v64, v67, v66
	v_div_fmas_f32 v64, v64, v65, v67
	v_div_fixup_f32 v58, v64, v58, 1.0
	v_mul_f32_e32 v48, v48, v58
	v_mul_f32_e32 v49, v49, v58
	v_mul_f32_e32 v50, v50, v58
	v_mul_f32_e32 v51, v51, v58
	v_cvt_pk_bf16_f32 v48, v48, v49
	v_cvt_pk_bf16_f32 v49, v50, v51
	global_store_dwordx2 v[20:21], v[48:49], off
	v_lshl_add_u64 v[20:21], v[20:21], 0, s[10:11]
	v_div_scale_f32 v64, s[16:17], v59, v59, 1.0
	v_rcp_f32_e32 v65, v64
	v_div_scale_f32 v66, vcc, 1.0, v59, 1.0
	v_fma_f32 v67, -v64, v65, 1.0
	v_fmac_f32_e32 v65, v67, v65
	v_mul_f32_e32 v67, v66, v65
	v_fma_f32 v68, -v64, v67, v66
	v_fmac_f32_e32 v67, v68, v65
	v_fma_f32 v64, -v64, v67, v66
	v_div_fmas_f32 v64, v64, v65, v67
	v_div_fixup_f32 v59, v64, v59, 1.0
	v_mul_f32_e32 v52, v52, v59
	v_mul_f32_e32 v53, v53, v59
	v_mul_f32_e32 v54, v54, v59
	v_mul_f32_e32 v55, v55, v59
	v_cvt_pk_bf16_f32 v52, v52, v53
	v_cvt_pk_bf16_f32 v53, v54, v55
	global_store_dwordx2 v[20:21], v[52:53], off
	v_lshl_add_u64 v[20:21], v[20:21], 0, s[10:11]
	global_load_dwordx4 v[40:43], v[4:5], off nt
	v_lshl_add_u64 v[4:5], v[4:5], 0, s[8:9]
	global_load_dwordx4 v[44:47], v[4:5], off nt
	v_lshl_add_u64 v[4:5], v[4:5], 0, s[8:9]
	global_load_dwordx4 v[48:51], v[4:5], off nt
	v_lshl_add_u64 v[4:5], v[4:5], 0, s[8:9]
	global_load_dwordx4 v[52:55], v[4:5], off nt
	v_lshl_add_u64 v[4:5], v[4:5], 0, s[8:9]
	s_waitcnt vmcnt(8)
	v_max_f32_e32 v56, v27, v27
	v_max_f32_e32 v60, v26, v26
	v_max_f32_e32 v56, v60, v56
	v_max3_f32 v56, v24, v25, v56
	v_max_f32_e32 v57, v31, v31
	v_max_f32_e32 v61, v30, v30
	v_max_f32_e32 v57, v61, v57
	v_max3_f32 v57, v28, v29, v57
	v_max_f32_e32 v58, v35, v35
	v_max_f32_e32 v62, v34, v34
	v_max_f32_e32 v58, v62, v58
	v_max3_f32 v58, v32, v33, v58
	v_max_f32_e32 v59, v39, v39
	v_max_f32_e32 v63, v38, v38
	v_max_f32_e32 v59, v63, v59
	v_max3_f32 v59, v36, v37, v59
	v_mov_b32_e32 v69, v56
	v_mov_b32_e32 v70, v56
	s_nop 1
	v_permlane32_swap_b32_e32 v69, v70
	v_cndmask_b32_e64 v60, v69, v70, s[18:19]
	v_mov_b32_e32 v69, v57
	v_mov_b32_e32 v70, v57
	s_nop 1
	v_permlane32_swap_b32_e32 v69, v70
	v_cndmask_b32_e64 v61, v69, v70, s[18:19]
	v_mov_b32_e32 v69, v58
	v_mov_b32_e32 v70, v58
	s_nop 1
	v_permlane32_swap_b32_e32 v69, v70
	v_cndmask_b32_e64 v62, v69, v70, s[18:19]
	v_mov_b32_e32 v69, v59
	v_mov_b32_e32 v70, v59
	s_nop 1
	v_permlane32_swap_b32_e32 v69, v70
	v_cndmask_b32_e64 v63, v69, v70, s[18:19]
	v_max_f32_e32 v60, v60, v60
	v_max_f32_e32 v56, v56, v60
	v_max_f32_e32 v61, v61, v61
	v_max_f32_e32 v57, v57, v61
	v_max_f32_e32 v62, v62, v62
	v_max_f32_e32 v58, v58, v62
	v_max_f32_e32 v63, v63, v63
	v_max_f32_e32 v59, v59, v63
	v_mov_b32_e32 v69, v56
	v_mov_b32_e32 v70, v56
	s_nop 1
	v_permlane16_swap_b32_e32 v69, v70
	v_cndmask_b32_e64 v60, v69, v70, s[20:21]
	v_mov_b32_e32 v69, v57
	v_mov_b32_e32 v70, v57
	s_nop 1
	v_permlane16_swap_b32_e32 v69, v70
	v_cndmask_b32_e64 v61, v69, v70, s[20:21]
	v_mov_b32_e32 v69, v58
	v_mov_b32_e32 v70, v58
	s_nop 1
	v_permlane16_swap_b32_e32 v69, v70
	v_cndmask_b32_e64 v62, v69, v70, s[20:21]
	v_mov_b32_e32 v69, v59
	v_mov_b32_e32 v70, v59
	s_nop 1
	v_permlane16_swap_b32_e32 v69, v70
; DEV float wave_sum(float v) {
; #pragma unroll
;     for (int o = 32; o >= 1; o >>= 1) v += __shfl_xor(v, o);
;     return v;
; }
; DEV float wave_max(float v) {
; #pragma unroll
;     for (int o = 32; o >= 1; o >>= 1) v = fmaxf(v, __shfl_xor(v, o));
;     return v;
; }
; __global__ void __launch_bounds__(512) hymba_fwd(Params p) {
;     ...
;         const float mx = wave_max(fmaxf(fmaxf(v[0], v[1]), fmaxf(v[2], v[3])));
;         f32x4 e; e[0] = __expf(v[0] - mx); e[1] = __expf(v[1] - mx); e[2] = __expf(v[2] - mx); e[3] = __expf(v[3] - mx);
;         const float inv = 1.f / wave_sum(e[0] + e[1] + e[2] + e[3]);
	v_cndmask_b32_e64 v63, v69, v70, s[20:21]
	v_max_f32_e32 v60, v60, v60
	v_max_f32_e32 v56, v56, v60
	v_max_f32_e32 v61, v61, v61
	v_max_f32_e32 v57, v57, v61
	v_max_f32_e32 v62, v62, v62
	v_max_f32_e32 v58, v58, v62
	v_max_f32_e32 v63, v63, v63
	v_max_f32_e32 v59, v59, v63
	v_mov_b32_dpp v60, v56 row_ror:8 row_mask:0xf bank_mask:0xf
	v_mov_b32_dpp v61, v57 row_ror:8 row_mask:0xf bank_mask:0xf
	v_mov_b32_dpp v62, v58 row_ror:8 row_mask:0xf bank_mask:0xf
	v_mov_b32_dpp v63, v59 row_ror:8 row_mask:0xf bank_mask:0xf
	v_max_f32_e32 v60, v60, v60
	v_max_f32_e32 v56, v56, v60
	v_max_f32_e32 v61, v61, v61
	v_max_f32_e32 v57, v57, v61
	v_max_f32_e32 v62, v62, v62
	v_max_f32_e32 v58, v58, v62
	v_max_f32_e32 v63, v63, v63
	v_max_f32_e32 v59, v59, v63
	v_mov_b32_dpp v69, v56 row_shr:4 row_mask:0xf bank_mask:0xa
	v_mov_b32_dpp v69, v56 row_shl:4 row_mask:0xf bank_mask:0x5
	v_mov_b32_e32 v60, v69
	v_mov_b32_dpp v69, v57 row_shr:4 row_mask:0xf bank_mask:0xa
	v_mov_b32_dpp v69, v57 row_shl:4 row_mask:0xf bank_mask:0x5
	v_mov_b32_e32 v61, v69
	v_mov_b32_dpp v69, v58 row_shr:4 row_mask:0xf bank_mask:0xa
	v_mov_b32_dpp v69, v58 row_shl:4 row_mask:0xf bank_mask:0x5
	v_mov_b32_e32 v62, v69
	v_mov_b32_dpp v69, v59 row_shr:4 row_mask:0xf bank_mask:0xa
	v_mov_b32_dpp v69, v59 row_shl:4 row_mask:0xf bank_mask:0x5
	v_mov_b32_e32 v63, v69
	v_max_f32_e32 v60, v60, v60
	v_max_f32_e32 v56, v56, v60
	v_max_f32_e32 v61, v61, v61
	v_max_f32_e32 v57, v57, v61
	v_max_f32_e32 v62, v62, v62
	v_max_f32_e32 v58, v58, v62
	v_max_f32_e32 v63, v63, v63
	v_max_f32_e32 v59, v59, v63
	v_mov_b32_dpp v60, v56 quad_perm:[2,3,0,1] row_mask:0xf bank_mask:0xf
	v_mov_b32_dpp v61, v57 quad_perm:[2,3,0,1] row_mask:0xf bank_mask:0xf
	v_mov_b32_dpp v62, v58 quad_perm:[2,3,0,1] row_mask:0xf bank_mask:0xf
	v_mov_b32_dpp v63, v59 quad_perm:[2,3,0,1] row_mask:0xf bank_mask:0xf
	v_max_f32_e32 v60, v60, v60
	v_max_f32_e32 v56, v56, v60
	v_max_f32_e32 v61, v61, v61
	v_max_f32_e32 v57, v57, v61
	v_max_f32_e32 v62, v62, v62
	v_max_f32_e32 v58, v58, v62
	v_max_f32_e32 v63, v63, v63
	v_max_f32_e32 v59, v59, v63
	v_mov_b32_dpp v60, v56 quad_perm:[1,0,3,2] row_mask:0xf bank_mask:0xf
	v_mov_b32_dpp v61, v57 quad_perm:[1,0,3,2] row_mask:0xf bank_mask:0xf
	v_mov_b32_dpp v62, v58 quad_perm:[1,0,3,2] row_mask:0xf bank_mask:0xf
	v_mov_b32_dpp v63, v59 quad_perm:[1,0,3,2] row_mask:0xf bank_mask:0xf
	v_max_f32_e32 v60, v60, v60
	v_max_f32_e32 v56, v56, v60
	v_max_f32_e32 v61, v61, v61
	v_max_f32_e32 v57, v57, v61
	v_max_f32_e32 v62, v62, v62
	v_max_f32_e32 v58, v58, v62
	v_max_f32_e32 v63, v63, v63
	v_max_f32_e32 v59, v59, v63
	v_sub_f32_e32 v24, v24, v56
	v_sub_f32_e32 v25, v25, v56
	v_sub_f32_e32 v26, v26, v56
	v_sub_f32_e32 v27, v27, v56
	v_mul_f32_e32 v24, 0x3fb8aa3b, v24
	v_mul_f32_e32 v25, 0x3fb8aa3b, v25
	v_mul_f32_e32 v26, 0x3fb8aa3b, v26
	v_mul_f32_e32 v27, 0x3fb8aa3b, v27
	v_sub_f32_e32 v28, v28, v57
	v_sub_f32_e32 v29, v29, v57
	v_sub_f32_e32 v30, v30, v57
	v_sub_f32_e32 v31, v31, v57
	v_mul_f32_e32 v28, 0x3fb8aa3b, v28
	v_mul_f32_e32 v29, 0x3fb8aa3b, v29
	v_mul_f32_e32 v30, 0x3fb8aa3b, v30
	v_mul_f32_e32 v31, 0x3fb8aa3b, v31
	v_sub_f32_e32 v32, v32, v58
	v_sub_f32_e32 v33, v33, v58
	v_sub_f32_e32 v34, v34, v58
	v_sub_f32_e32 v35, v35, v58
	v_mul_f32_e32 v32, 0x3fb8aa3b, v32
	v_mul_f32_e32 v33, 0x3fb8aa3b, v33
	v_mul_f32_e32 v34, 0x3fb8aa3b, v34
	v_mul_f32_e32 v35, 0x3fb8aa3b, v35
	v_sub_f32_e32 v36, v36, v59
	v_sub_f32_e32 v37, v37, v59
	v_sub_f32_e32 v38, v38, v59
	v_sub_f32_e32 v39, v39, v59
	v_mul_f32_e32 v36, 0x3fb8aa3b, v36
	v_mul_f32_e32 v37, 0x3fb8aa3b, v37
	v_mul_f32_e32 v38, 0x3fb8aa3b, v38
	v_mul_f32_e32 v39, 0x3fb8aa3b, v39
	v_exp_f32_e32 v24, v24
	v_exp_f32_e32 v25, v25
	v_exp_f32_e32 v26, v26
	v_exp_f32_e32 v27, v27
	v_exp_f32_e32 v28, v28
	v_exp_f32_e32 v29, v29
	v_exp_f32_e32 v30, v30
	v_exp_f32_e32 v31, v31
	v_exp_f32_e32 v32, v32
	v_exp_f32_e32 v33, v33
	v_exp_f32_e32 v34, v34
	v_exp_f32_e32 v35, v35
	v_exp_f32_e32 v36, v36
	v_exp_f32_e32 v37, v37
	v_exp_f32_e32 v38, v38
	v_exp_f32_e32 v39, v39
	v_add_f32_e32 v56, v24, v25
	v_add_f32_e32 v56, v26, v56
	v_add_f32_e32 v56, v27, v56
	v_add_f32_e32 v57, v28, v29
	v_add_f32_e32 v57, v30, v57
	v_add_f32_e32 v57, v31, v57
	v_add_f32_e32 v58, v32, v33
	v_add_f32_e32 v58, v34, v58
	v_add_f32_e32 v58, v35, v58
	v_add_f32_e32 v59, v36, v37
	v_add_f32_e32 v59, v38, v59
	v_add_f32_e32 v59, v39, v59
	v_mov_b32_e32 v69, v56
	v_mov_b32_e32 v70, v56
	s_nop 1
	v_permlane32_swap_b32_e32 v69, v70
	v_cndmask_b32_e64 v60, v69, v70, s[18:19]
	v_mov_b32_e32 v69, v57
	v_mov_b32_e32 v70, v57
	s_nop 1
	v_permlane32_swap_b32_e32 v69, v70
	v_cndmask_b32_e64 v61, v69, v70, s[18:19]
	v_mov_b32_e32 v69, v58
	v_mov_b32_e32 v70, v58
	s_nop 1
	v_permlane32_swap_b32_e32 v69, v70
	v_cndmask_b32_e64 v62, v69, v70, s[18:19]
	v_mov_b32_e32 v69, v59
	v_mov_b32_e32 v70, v59
	s_nop 1
	v_permlane32_swap_b32_e32 v69, v70
	v_cndmask_b32_e64 v63, v69, v70, s[18:19]
	v_add_f32_e32 v56, v56, v60
	v_add_f32_e32 v57, v57, v61
	v_add_f32_e32 v58, v58, v62
	v_add_f32_e32 v59, v59, v63
	v_mov_b32_e32 v69, v56
	v_mov_b32_e32 v70, v56
	s_nop 1
	v_permlane16_swap_b32_e32 v69, v70
	v_cndmask_b32_e64 v60, v69, v70, s[20:21]
	v_mov_b32_e32 v69, v57
	v_mov_b32_e32 v70, v57
	s_nop 1
	v_permlane16_swap_b32_e32 v69, v70
	v_cndmask_b32_e64 v61, v69, v70, s[20:21]
	v_mov_b32_e32 v69, v58
	v_mov_b32_e32 v70, v58
	s_nop 1
	v_permlane16_swap_b32_e32 v69, v70
	v_cndmask_b32_e64 v62, v69, v70, s[20:21]
	v_mov_b32_e32 v69, v59
	v_mov_b32_e32 v70, v59
	s_nop 1
	v_permlane16_swap_b32_e32 v69, v70
	v_cndmask_b32_e64 v63, v69, v70, s[20:21]
	v_add_f32_e32 v56, v56, v60
	v_add_f32_e32 v57, v57, v61
; DEV void store_bf4(bf16_t* p, f32x4 v) { uint2 w; w.x = cvt_pk_bf16(v[0], v[1]); w.y = cvt_pk_bf16(v[2], v[3]); *(uint2*)p = w; }
; DEV float wave_sum(float v) {
; #pragma unroll
;     for (int o = 32; o >= 1; o >>= 1) v += __shfl_xor(v, o);
;     return v;
; }
; __global__ void __launch_bounds__(512) hymba_fwd(Params p) {
;     ...
;     for (int r = bid * 8 + wid; r < TP * 4; r += G * 8) {
;         const f32x4 v = __builtin_nontemporal_load((const f32x4*)(sc + (size_t)r * 256 + lane * 4));
;         const float mx = wave_max(fmaxf(fmaxf(v[0], v[1]), fmaxf(v[2], v[3])));
;         f32x4 e; e[0] = __expf(v[0] - mx); e[1] = __expf(v[1] - mx); e[2] = __expf(v[2] - mx); e[3] = __expf(v[3] - mx);
;         const float inv = 1.f / wave_sum(e[0] + e[1] + e[2] + e[3]);
;         store_bf4(pb + (size_t)(r >> 2) * LDP + (r & 3) * 256 + lane * 4, e * inv);
;     }
	v_add_f32_e32 v58, v58, v62
	v_add_f32_e32 v59, v59, v63
	v_mov_b32_dpp v60, v56 row_ror:8 row_mask:0xf bank_mask:0xf
	v_mov_b32_dpp v61, v57 row_ror:8 row_mask:0xf bank_mask:0xf
	v_mov_b32_dpp v62, v58 row_ror:8 row_mask:0xf bank_mask:0xf
	v_mov_b32_dpp v63, v59 row_ror:8 row_mask:0xf bank_mask:0xf
	v_add_f32_e32 v56, v56, v60
	v_add_f32_e32 v57, v57, v61
	v_add_f32_e32 v58, v58, v62
	v_add_f32_e32 v59, v59, v63
	v_mov_b32_dpp v69, v56 row_shr:4 row_mask:0xf bank_mask:0xa
	v_mov_b32_dpp v69, v56 row_shl:4 row_mask:0xf bank_mask:0x5
	v_mov_b32_e32 v60, v69
	v_mov_b32_dpp v69, v57 row_shr:4 row_mask:0xf bank_mask:0xa
	v_mov_b32_dpp v69, v57 row_shl:4 row_mask:0xf bank_mask:0x5
	v_mov_b32_e32 v61, v69
	v_mov_b32_dpp v69, v58 row_shr:4 row_mask:0xf bank_mask:0xa
	v_mov_b32_dpp v69, v58 row_shl:4 row_mask:0xf bank_mask:0x5
	v_mov_b32_e32 v62, v69
	v_mov_b32_dpp v69, v59 row_shr:4 row_mask:0xf bank_mask:0xa
	v_mov_b32_dpp v69, v59 row_shl:4 row_mask:0xf bank_mask:0x5
	v_mov_b32_e32 v63, v69
	v_add_f32_e32 v56, v56, v60
	v_add_f32_e32 v57, v57, v61
	v_add_f32_e32 v58, v58, v62
	v_add_f32_e32 v59, v59, v63
	v_mov_b32_dpp v60, v56 quad_perm:[2,3,0,1] row_mask:0xf bank_mask:0xf
	v_mov_b32_dpp v61, v57 quad_perm:[2,3,0,1] row_mask:0xf bank_mask:0xf
	v_mov_b32_dpp v62, v58 quad_perm:[2,3,0,1] row_mask:0xf bank_mask:0xf
	v_mov_b32_dpp v63, v59 quad_perm:[2,3,0,1] row_mask:0xf bank_mask:0xf
	v_add_f32_e32 v56, v56, v60
	v_add_f32_e32 v57, v57, v61
	v_add_f32_e32 v58, v58, v62
	v_add_f32_e32 v59, v59, v63
	v_mov_b32_dpp v60, v56 quad_perm:[1,0,3,2] row_mask:0xf bank_mask:0xf
	v_mov_b32_dpp v61, v57 quad_perm:[1,0,3,2] row_mask:0xf bank_mask:0xf
	v_mov_b32_dpp v62, v58 quad_perm:[1,0,3,2] row_mask:0xf bank_mask:0xf
	v_mov_b32_dpp v63, v59 quad_perm:[1,0,3,2] row_mask:0xf bank_mask:0xf
	v_add_f32_e32 v56, v56, v60
	v_add_f32_e32 v57, v57, v61
	v_add_f32_e32 v58, v58, v62
	v_add_f32_e32 v59, v59, v63
	v_div_scale_f32 v64, s[16:17], v56, v56, 1.0
	v_rcp_f32_e32 v65, v64
	v_div_scale_f32 v66, vcc, 1.0, v56, 1.0
	v_fma_f32 v67, -v64, v65, 1.0
	v_fmac_f32_e32 v65, v67, v65
	v_mul_f32_e32 v67, v66, v65
	v_fma_f32 v68, -v64, v67, v66
	v_fmac_f32_e32 v67, v68, v65
	v_fma_f32 v64, -v64, v67, v66
	v_div_fmas_f32 v64, v64, v65, v67
	v_div_fixup_f32 v56, v64, v56, 1.0
	v_mul_f32_e32 v24, v24, v56
	v_mul_f32_e32 v25, v25, v56
	v_mul_f32_e32 v26, v26, v56
	v_mul_f32_e32 v27, v27, v56
	v_cvt_pk_bf16_f32 v24, v24, v25
	v_cvt_pk_bf16_f32 v25, v26, v27
	global_store_dwordx2 v[20:21], v[24:25], off
	v_lshl_add_u64 v[20:21], v[20:21], 0, s[10:11]
	v_div_scale_f32 v64, s[16:17], v57, v57, 1.0
	v_rcp_f32_e32 v65, v64
	v_div_scale_f32 v66, vcc, 1.0, v57, 1.0
	v_fma_f32 v67, -v64, v65, 1.0
	v_fmac_f32_e32 v65, v67, v65
	v_mul_f32_e32 v67, v66, v65
	v_fma_f32 v68, -v64, v67, v66
	v_fmac_f32_e32 v67, v68, v65
	v_fma_f32 v64, -v64, v67, v66
	v_div_fmas_f32 v64, v64, v65, v67
	v_div_fixup_f32 v57, v64, v57, 1.0
	v_mul_f32_e32 v28, v28, v57
	v_mul_f32_e32 v29, v29, v57
	v_mul_f32_e32 v30, v30, v57
	v_mul_f32_e32 v31, v31, v57
	v_cvt_pk_bf16_f32 v28, v28, v29
	v_cvt_pk_bf16_f32 v29, v30, v31
	global_store_dwordx2 v[20:21], v[28:29], off
	v_lshl_add_u64 v[20:21], v[20:21], 0, s[10:11]
	v_div_scale_f32 v64, s[16:17], v58, v58, 1.0
	v_rcp_f32_e32 v65, v64
	v_div_scale_f32 v66, vcc, 1.0, v58, 1.0
	v_fma_f32 v67, -v64, v65, 1.0
	v_fmac_f32_e32 v65, v67, v65
	v_mul_f32_e32 v67, v66, v65
	v_fma_f32 v68, -v64, v67, v66
	v_fmac_f32_e32 v67, v68, v65
	v_fma_f32 v64, -v64, v67, v66
	v_div_fmas_f32 v64, v64, v65, v67
	v_div_fixup_f32 v58, v64, v58, 1.0
	v_mul_f32_e32 v32, v32, v58
	v_mul_f32_e32 v33, v33, v58
	v_mul_f32_e32 v34, v34, v58
	v_mul_f32_e32 v35, v35, v58
	v_cvt_pk_bf16_f32 v32, v32, v33
	v_cvt_pk_bf16_f32 v33, v34, v35
	global_store_dwordx2 v[20:21], v[32:33], off
	v_lshl_add_u64 v[20:21], v[20:21], 0, s[10:11]
	v_div_scale_f32 v64, s[16:17], v59, v59, 1.0
	v_rcp_f32_e32 v65, v64
	v_div_scale_f32 v66, vcc, 1.0, v59, 1.0
	v_fma_f32 v67, -v64, v65, 1.0
	v_fmac_f32_e32 v65, v67, v65
	v_mul_f32_e32 v67, v66, v65
	v_fma_f32 v68, -v64, v67, v66
	v_fmac_f32_e32 v67, v68, v65
	v_fma_f32 v64, -v64, v67, v66
	v_div_fmas_f32 v64, v64, v65, v67
	v_div_fixup_f32 v59, v64, v59, 1.0
	v_mul_f32_e32 v36, v36, v59
	v_mul_f32_e32 v37, v37, v59
	v_mul_f32_e32 v38, v38, v59
	v_mul_f32_e32 v39, v39, v59
	v_cvt_pk_bf16_f32 v36, v36, v37
	v_cvt_pk_bf16_f32 v37, v38, v39
	global_store_dwordx2 v[20:21], v[36:37], off
	v_lshl_add_u64 v[20:21], v[20:21], 0, s[10:11]
	s_waitcnt vmcnt(4)
; DEV float wave_max(float v) {
; #pragma unroll
;     for (int o = 32; o >= 1; o >>= 1) v = fmaxf(v, __shfl_xor(v, o));
;     return v;
; }
; __global__ void __launch_bounds__(512) hymba_fwd(Params p) {
;     ...
;     for (int r = bid * 8 + wid; r < TP * 4; r += G * 8) {
;         const f32x4 v = __builtin_nontemporal_load((const f32x4*)(sc + (size_t)r * 256 + lane * 4));
;         const float mx = wave_max(fmaxf(fmaxf(v[0], v[1]), fmaxf(v[2], v[3])));
;         f32x4 e; e[0] = __expf(v[0] - mx); e[1] = __expf(v[1] - mx); e[2] = __expf(v[2] - mx); e[3] = __expf(v[3] - mx);
	v_max_f32_e32 v56, v43, v43
	v_max_f32_e32 v60, v42, v42
	v_max_f32_e32 v56, v60, v56
	v_max3_f32 v56, v40, v41, v56
	v_max_f32_e32 v57, v47, v47
	v_max_f32_e32 v61, v46, v46
	v_max_f32_e32 v57, v61, v57
	v_max3_f32 v57, v44, v45, v57
	v_max_f32_e32 v58, v51, v51
	v_max_f32_e32 v62, v50, v50
	v_max_f32_e32 v58, v62, v58
	v_max3_f32 v58, v48, v49, v58
	v_max_f32_e32 v59, v55, v55
	v_max_f32_e32 v63, v54, v54
	v_max_f32_e32 v59, v63, v59
	v_max3_f32 v59, v52, v53, v59
	v_mov_b32_e32 v69, v56
	v_mov_b32_e32 v70, v56
	s_nop 1
	v_permlane32_swap_b32_e32 v69, v70
	v_cndmask_b32_e64 v60, v69, v70, s[18:19]
	v_mov_b32_e32 v69, v57
	v_mov_b32_e32 v70, v57
	s_nop 1
	v_permlane32_swap_b32_e32 v69, v70
	v_cndmask_b32_e64 v61, v69, v70, s[18:19]
	v_mov_b32_e32 v69, v58
	v_mov_b32_e32 v70, v58
	s_nop 1
	v_permlane32_swap_b32_e32 v69, v70
	v_cndmask_b32_e64 v62, v69, v70, s[18:19]
	v_mov_b32_e32 v69, v59
	v_mov_b32_e32 v70, v59
	s_nop 1
	v_permlane32_swap_b32_e32 v69, v70
	v_cndmask_b32_e64 v63, v69, v70, s[18:19]
	v_max_f32_e32 v60, v60, v60
	v_max_f32_e32 v56, v56, v60
	v_max_f32_e32 v61, v61, v61
	v_max_f32_e32 v57, v57, v61
	v_max_f32_e32 v62, v62, v62
	v_max_f32_e32 v58, v58, v62
	v_max_f32_e32 v63, v63, v63
	v_max_f32_e32 v59, v59, v63
	v_mov_b32_e32 v69, v56
	v_mov_b32_e32 v70, v56
	s_nop 1
	v_permlane16_swap_b32_e32 v69, v70
	v_cndmask_b32_e64 v60, v69, v70, s[20:21]
	v_mov_b32_e32 v69, v57
	v_mov_b32_e32 v70, v57
	s_nop 1
	v_permlane16_swap_b32_e32 v69, v70
	v_cndmask_b32_e64 v61, v69, v70, s[20:21]
	v_mov_b32_e32 v69, v58
	v_mov_b32_e32 v70, v58
	s_nop 1
	v_permlane16_swap_b32_e32 v69, v70
	v_cndmask_b32_e64 v62, v69, v70, s[20:21]
	v_mov_b32_e32 v69, v59
	v_mov_b32_e32 v70, v59
	s_nop 1
	v_permlane16_swap_b32_e32 v69, v70
	v_cndmask_b32_e64 v63, v69, v70, s[20:21]
	v_max_f32_e32 v60, v60, v60
	v_max_f32_e32 v56, v56, v60
	v_max_f32_e32 v61, v61, v61
	v_max_f32_e32 v57, v57, v61
	v_max_f32_e32 v62, v62, v62
	v_max_f32_e32 v58, v58, v62
	v_max_f32_e32 v63, v63, v63
	v_max_f32_e32 v59, v59, v63
	v_mov_b32_dpp v60, v56 row_ror:8 row_mask:0xf bank_mask:0xf
	v_mov_b32_dpp v61, v57 row_ror:8 row_mask:0xf bank_mask:0xf
	v_mov_b32_dpp v62, v58 row_ror:8 row_mask:0xf bank_mask:0xf
	v_mov_b32_dpp v63, v59 row_ror:8 row_mask:0xf bank_mask:0xf
	v_max_f32_e32 v60, v60, v60
	v_max_f32_e32 v56, v56, v60
	v_max_f32_e32 v61, v61, v61
	v_max_f32_e32 v57, v57, v61
	v_max_f32_e32 v62, v62, v62
	v_max_f32_e32 v58, v58, v62
	v_max_f32_e32 v63, v63, v63
	v_max_f32_e32 v59, v59, v63
	v_mov_b32_dpp v69, v56 row_shr:4 row_mask:0xf bank_mask:0xa
	v_mov_b32_dpp v69, v56 row_shl:4 row_mask:0xf bank_mask:0x5
	v_mov_b32_e32 v60, v69
	v_mov_b32_dpp v69, v57 row_shr:4 row_mask:0xf bank_mask:0xa
	v_mov_b32_dpp v69, v57 row_shl:4 row_mask:0xf bank_mask:0x5
	v_mov_b32_e32 v61, v69
	v_mov_b32_dpp v69, v58 row_shr:4 row_mask:0xf bank_mask:0xa
	v_mov_b32_dpp v69, v58 row_shl:4 row_mask:0xf bank_mask:0x5
	v_mov_b32_e32 v62, v69
	v_mov_b32_dpp v69, v59 row_shr:4 row_mask:0xf bank_mask:0xa
	v_mov_b32_dpp v69, v59 row_shl:4 row_mask:0xf bank_mask:0x5
	v_mov_b32_e32 v63, v69
	v_max_f32_e32 v60, v60, v60
	v_max_f32_e32 v56, v56, v60
	v_max_f32_e32 v61, v61, v61
	v_max_f32_e32 v57, v57, v61
	v_max_f32_e32 v62, v62, v62
	v_max_f32_e32 v58, v58, v62
	v_max_f32_e32 v63, v63, v63
	v_max_f32_e32 v59, v59, v63
	v_mov_b32_dpp v60, v56 quad_perm:[2,3,0,1] row_mask:0xf bank_mask:0xf
	v_mov_b32_dpp v61, v57 quad_perm:[2,3,0,1] row_mask:0xf bank_mask:0xf
	v_mov_b32_dpp v62, v58 quad_perm:[2,3,0,1] row_mask:0xf bank_mask:0xf
	v_mov_b32_dpp v63, v59 quad_perm:[2,3,0,1] row_mask:0xf bank_mask:0xf
	v_max_f32_e32 v60, v60, v60
	v_max_f32_e32 v56, v56, v60
	v_max_f32_e32 v61, v61, v61
	v_max_f32_e32 v57, v57, v61
	v_max_f32_e32 v62, v62, v62
	v_max_f32_e32 v58, v58, v62
	v_max_f32_e32 v63, v63, v63
	v_max_f32_e32 v59, v59, v63
	v_mov_b32_dpp v60, v56 quad_perm:[1,0,3,2] row_mask:0xf bank_mask:0xf
	v_mov_b32_dpp v61, v57 quad_perm:[1,0,3,2] row_mask:0xf bank_mask:0xf
	v_mov_b32_dpp v62, v58 quad_perm:[1,0,3,2] row_mask:0xf bank_mask:0xf
	v_mov_b32_dpp v63, v59 quad_perm:[1,0,3,2] row_mask:0xf bank_mask:0xf
	v_max_f32_e32 v60, v60, v60
	v_max_f32_e32 v56, v56, v60
	v_max_f32_e32 v61, v61, v61
	v_max_f32_e32 v57, v57, v61
	v_max_f32_e32 v62, v62, v62
	v_max_f32_e32 v58, v58, v62
	v_max_f32_e32 v63, v63, v63
	v_max_f32_e32 v59, v59, v63
	v_sub_f32_e32 v40, v40, v56
	v_sub_f32_e32 v41, v41, v56
	v_sub_f32_e32 v42, v42, v56
	v_sub_f32_e32 v43, v43, v56
	v_mul_f32_e32 v40, 0x3fb8aa3b, v40
	v_mul_f32_e32 v41, 0x3fb8aa3b, v41
	v_mul_f32_e32 v42, 0x3fb8aa3b, v42
	v_mul_f32_e32 v43, 0x3fb8aa3b, v43
	v_sub_f32_e32 v44, v44, v57
	v_sub_f32_e32 v45, v45, v57
	v_sub_f32_e32 v46, v46, v57
	v_sub_f32_e32 v47, v47, v57
	v_mul_f32_e32 v44, 0x3fb8aa3b, v44
	v_mul_f32_e32 v45, 0x3fb8aa3b, v45
	v_mul_f32_e32 v46, 0x3fb8aa3b, v46
	v_mul_f32_e32 v47, 0x3fb8aa3b, v47
	v_sub_f32_e32 v48, v48, v58
	v_sub_f32_e32 v49, v49, v58
	v_sub_f32_e32 v50, v50, v58
	v_sub_f32_e32 v51, v51, v58
	v_mul_f32_e32 v48, 0x3fb8aa3b, v48
	v_mul_f32_e32 v49, 0x3fb8aa3b, v49
	v_mul_f32_e32 v50, 0x3fb8aa3b, v50
	v_mul_f32_e32 v51, 0x3fb8aa3b, v51
	v_sub_f32_e32 v52, v52, v59
	v_sub_f32_e32 v53, v53, v59
	v_sub_f32_e32 v54, v54, v59
	v_sub_f32_e32 v55, v55, v59
	v_mul_f32_e32 v52, 0x3fb8aa3b, v52
	v_mul_f32_e32 v53, 0x3fb8aa3b, v53
	v_mul_f32_e32 v54, 0x3fb8aa3b, v54
	v_mul_f32_e32 v55, 0x3fb8aa3b, v55
	v_exp_f32_e32 v40, v40
	v_exp_f32_e32 v41, v41
	v_exp_f32_e32 v42, v42
	v_exp_f32_e32 v43, v43
	v_exp_f32_e32 v44, v44
	v_exp_f32_e32 v45, v45
	v_exp_f32_e32 v46, v46
	v_exp_f32_e32 v47, v47
	v_exp_f32_e32 v48, v48
	v_exp_f32_e32 v49, v49
; DEV void store_bf4(bf16_t* p, f32x4 v) { uint2 w; w.x = cvt_pk_bf16(v[0], v[1]); w.y = cvt_pk_bf16(v[2], v[3]); *(uint2*)p = w; }
; DEV float wave_sum(float v) {
; #pragma unroll
;     for (int o = 32; o >= 1; o >>= 1) v += __shfl_xor(v, o);
;     return v;
; }
; __global__ void __launch_bounds__(512) hymba_fwd(Params p) {
;     ...
;         f32x4 e; e[0] = __expf(v[0] - mx); e[1] = __expf(v[1] - mx); e[2] = __expf(v[2] - mx); e[3] = __expf(v[3] - mx);
;         const float inv = 1.f / wave_sum(e[0] + e[1] + e[2] + e[3]);
;         store_bf4(pb + (size_t)(r >> 2) * LDP + (r & 3) * 256 + lane * 4, e * inv);
;     }
	v_exp_f32_e32 v50, v50
	v_exp_f32_e32 v51, v51
	v_exp_f32_e32 v52, v52
	v_exp_f32_e32 v53, v53
	v_exp_f32_e32 v54, v54
	v_exp_f32_e32 v55, v55
	v_add_f32_e32 v56, v40, v41
	v_add_f32_e32 v56, v42, v56
	v_add_f32_e32 v56, v43, v56
	v_add_f32_e32 v57, v44, v45
	v_add_f32_e32 v57, v46, v57
	v_add_f32_e32 v57, v47, v57
	v_add_f32_e32 v58, v48, v49
	v_add_f32_e32 v58, v50, v58
	v_add_f32_e32 v58, v51, v58
	v_add_f32_e32 v59, v52, v53
	v_add_f32_e32 v59, v54, v59
	v_add_f32_e32 v59, v55, v59
	v_mov_b32_e32 v69, v56
	v_mov_b32_e32 v70, v56
	s_nop 1
	v_permlane32_swap_b32_e32 v69, v70
	v_cndmask_b32_e64 v60, v69, v70, s[18:19]
	v_mov_b32_e32 v69, v57
	v_mov_b32_e32 v70, v57
	s_nop 1
	v_permlane32_swap_b32_e32 v69, v70
	v_cndmask_b32_e64 v61, v69, v70, s[18:19]
	v_mov_b32_e32 v69, v58
	v_mov_b32_e32 v70, v58
	s_nop 1
	v_permlane32_swap_b32_e32 v69, v70
	v_cndmask_b32_e64 v62, v69, v70, s[18:19]
	v_mov_b32_e32 v69, v59
	v_mov_b32_e32 v70, v59
	s_nop 1
	v_permlane32_swap_b32_e32 v69, v70
	v_cndmask_b32_e64 v63, v69, v70, s[18:19]
	v_add_f32_e32 v56, v56, v60
	v_add_f32_e32 v57, v57, v61
	v_add_f32_e32 v58, v58, v62
	v_add_f32_e32 v59, v59, v63
	v_mov_b32_e32 v69, v56
	v_mov_b32_e32 v70, v56
	s_nop 1
	v_permlane16_swap_b32_e32 v69, v70
	v_cndmask_b32_e64 v60, v69, v70, s[20:21]
	v_mov_b32_e32 v69, v57
	v_mov_b32_e32 v70, v57
	s_nop 1
	v_permlane16_swap_b32_e32 v69, v70
	v_cndmask_b32_e64 v61, v69, v70, s[20:21]
	v_mov_b32_e32 v69, v58
	v_mov_b32_e32 v70, v58
	s_nop 1
	v_permlane16_swap_b32_e32 v69, v70
	v_cndmask_b32_e64 v62, v69, v70, s[20:21]
	v_mov_b32_e32 v69, v59
	v_mov_b32_e32 v70, v59
	s_nop 1
	v_permlane16_swap_b32_e32 v69, v70
	v_cndmask_b32_e64 v63, v69, v70, s[20:21]
	v_add_f32_e32 v56, v56, v60
	v_add_f32_e32 v57, v57, v61
	v_add_f32_e32 v58, v58, v62
	v_add_f32_e32 v59, v59, v63
	v_mov_b32_dpp v60, v56 row_ror:8 row_mask:0xf bank_mask:0xf
	v_mov_b32_dpp v61, v57 row_ror:8 row_mask:0xf bank_mask:0xf
	v_mov_b32_dpp v62, v58 row_ror:8 row_mask:0xf bank_mask:0xf
	v_mov_b32_dpp v63, v59 row_ror:8 row_mask:0xf bank_mask:0xf
	v_add_f32_e32 v56, v56, v60
	v_add_f32_e32 v57, v57, v61
	v_add_f32_e32 v58, v58, v62
	v_add_f32_e32 v59, v59, v63
	v_mov_b32_dpp v69, v56 row_shr:4 row_mask:0xf bank_mask:0xa
	v_mov_b32_dpp v69, v56 row_shl:4 row_mask:0xf bank_mask:0x5
	v_mov_b32_e32 v60, v69
	v_mov_b32_dpp v69, v57 row_shr:4 row_mask:0xf bank_mask:0xa
	v_mov_b32_dpp v69, v57 row_shl:4 row_mask:0xf bank_mask:0x5
	v_mov_b32_e32 v61, v69
	v_mov_b32_dpp v69, v58 row_shr:4 row_mask:0xf bank_mask:0xa
	v_mov_b32_dpp v69, v58 row_shl:4 row_mask:0xf bank_mask:0x5
	v_mov_b32_e32 v62, v69
	v_mov_b32_dpp v69, v59 row_shr:4 row_mask:0xf bank_mask:0xa
	v_mov_b32_dpp v69, v59 row_shl:4 row_mask:0xf bank_mask:0x5
	v_mov_b32_e32 v63, v69
	v_add_f32_e32 v56, v56, v60
	v_add_f32_e32 v57, v57, v61
	v_add_f32_e32 v58, v58, v62
	v_add_f32_e32 v59, v59, v63
	v_mov_b32_dpp v60, v56 quad_perm:[2,3,0,1] row_mask:0xf bank_mask:0xf
	v_mov_b32_dpp v61, v57 quad_perm:[2,3,0,1] row_mask:0xf bank_mask:0xf
	v_mov_b32_dpp v62, v58 quad_perm:[2,3,0,1] row_mask:0xf bank_mask:0xf
	v_mov_b32_dpp v63, v59 quad_perm:[2,3,0,1] row_mask:0xf bank_mask:0xf
	v_add_f32_e32 v56, v56, v60
	v_add_f32_e32 v57, v57, v61
	v_add_f32_e32 v58, v58, v62
	v_add_f32_e32 v59, v59, v63
	v_mov_b32_dpp v60, v56 quad_perm:[1,0,3,2] row_mask:0xf bank_mask:0xf
	v_mov_b32_dpp v61, v57 quad_perm:[1,0,3,2] row_mask:0xf bank_mask:0xf
	v_mov_b32_dpp v62, v58 quad_perm:[1,0,3,2] row_mask:0xf bank_mask:0xf
	v_mov_b32_dpp v63, v59 quad_perm:[1,0,3,2] row_mask:0xf bank_mask:0xf
	v_add_f32_e32 v56, v56, v60
	v_add_f32_e32 v57, v57, v61
	v_add_f32_e32 v58, v58, v62
	v_add_f32_e32 v59, v59, v63
	v_div_scale_f32 v64, s[16:17], v56, v56, 1.0
	v_rcp_f32_e32 v65, v64
	v_div_scale_f32 v66, vcc, 1.0, v56, 1.0
	v_fma_f32 v67, -v64, v65, 1.0
	v_fmac_f32_e32 v65, v67, v65
	v_mul_f32_e32 v67, v66, v65
	v_fma_f32 v68, -v64, v67, v66
	v_fmac_f32_e32 v67, v68, v65
	v_fma_f32 v64, -v64, v67, v66
	v_div_fmas_f32 v64, v64, v65, v67
	v_div_fixup_f32 v56, v64, v56, 1.0
	v_mul_f32_e32 v40, v40, v56
	v_mul_f32_e32 v41, v41, v56
	v_mul_f32_e32 v42, v42, v56
	v_mul_f32_e32 v43, v43, v56
	v_cvt_pk_bf16_f32 v40, v40, v41
	v_cvt_pk_bf16_f32 v41, v42, v43
	global_store_dwordx2 v[20:21], v[40:41], off
	v_lshl_add_u64 v[20:21], v[20:21], 0, s[10:11]
	v_div_scale_f32 v64, s[16:17], v57, v57, 1.0
	v_rcp_f32_e32 v65, v64
	v_div_scale_f32 v66, vcc, 1.0, v57, 1.0
	v_fma_f32 v67, -v64, v65, 1.0
	v_fmac_f32_e32 v65, v67, v65
	v_mul_f32_e32 v67, v66, v65
	v_fma_f32 v68, -v64, v67, v66
	v_fmac_f32_e32 v67, v68, v65
	v_fma_f32 v64, -v64, v67, v66
	v_div_fmas_f32 v64, v64, v65, v67
	v_div_fixup_f32 v57, v64, v57, 1.0
	v_mul_f32_e32 v44, v44, v57
	v_mul_f32_e32 v45, v45, v57
	v_mul_f32_e32 v46, v46, v57
	v_mul_f32_e32 v47, v47, v57
	v_cvt_pk_bf16_f32 v44, v44, v45
	v_cvt_pk_bf16_f32 v45, v46, v47
	global_store_dwordx2 v[20:21], v[44:45], off
	v_lshl_add_u64 v[20:21], v[20:21], 0, s[10:11]
	v_div_scale_f32 v64, s[16:17], v58, v58, 1.0
	v_rcp_f32_e32 v65, v64
	v_div_scale_f32 v66, vcc, 1.0, v58, 1.0
	v_fma_f32 v67, -v64, v65, 1.0
	v_fmac_f32_e32 v65, v67, v65
	v_mul_f32_e32 v67, v66, v65
	v_fma_f32 v68, -v64, v67, v66
	v_fmac_f32_e32 v67, v68, v65
	v_fma_f32 v64, -v64, v67, v66
	v_div_fmas_f32 v64, v64, v65, v67
	v_div_fixup_f32 v58, v64, v58, 1.0
	v_mul_f32_e32 v48, v48, v58
	v_mul_f32_e32 v49, v49, v58
	v_mul_f32_e32 v50, v50, v58
	v_mul_f32_e32 v51, v51, v58
	v_cvt_pk_bf16_f32 v48, v48, v49
	v_cvt_pk_bf16_f32 v49, v50, v51
	global_store_dwordx2 v[20:21], v[48:49], off
	v_lshl_add_u64 v[20:21], v[20:21], 0, s[10:11]
	v_div_scale_f32 v64, s[16:17], v59, v59, 1.0
	v_rcp_f32_e32 v65, v64
	v_div_scale_f32 v66, vcc, 1.0, v59, 1.0
	v_fma_f32 v67, -v64, v65, 1.0
	v_fmac_f32_e32 v65, v67, v65
	v_mul_f32_e32 v67, v66, v65
	v_fma_f32 v68, -v64, v67, v66
	v_fmac_f32_e32 v67, v68, v65
	v_fma_f32 v64, -v64, v67, v66
	v_div_fmas_f32 v64, v64, v65, v67
	v_div_fixup_f32 v59, v64, v59, 1.0
	v_mul_f32_e32 v52, v52, v59
	v_mul_f32_e32 v53, v53, v59
	v_mul_f32_e32 v54, v54, v59
	v_mul_f32_e32 v55, v55, v59
	v_cvt_pk_bf16_f32 v52, v52, v53
	v_cvt_pk_bf16_f32 v53, v54, v55
	global_store_dwordx2 v[20:21], v[52:53], off
	v_lshl_add_u64 v[20:21], v[20:21], 0, s[10:11]
	s_waitcnt vmcnt(0)
	s_barrier
	s_mov_b64 s[6:7], 0x20f39000
	v_lshl_add_u64 v[86:87], v[158:159], 0, s[6:7]
	s_branch .Lp10_guard
